# GEMM epilogues through LDS: P8 Qp, P1 Q/K/V^T and P6 Z1 written with full-line dwordx4 stores (P6: x loads batched 8 deep instead of one exposed load per fragment)
# speedup vs baseline: 1.0128x; 1.0128x over previous
; template <class Epi>
; DI void gemm_tile256(const u16* __restrict__ Ag, long lda, const u16* __restrict__ Bg, long ldb, int nk, char* shm, Epi&& epi) {
;     ...
;   for (int i = 0; i < nk; ++i) {
;     if (i + 2 < nk) asm volatile("s_waitcnt vmcnt(8)" ::: "memory");
;     else if (i + 1 < nk) asm volatile("s_waitcnt vmcnt(4)" ::: "memory");
;     else asm volatile("s_waitcnt vmcnt(0)" ::: "memory");
;     __builtin_amdgcn_s_barrier();
;     const char* SA = shm + (i & 3) * 32768; const char* SB = SA + 16384;
;     bf16x8 At[8], Bt[4];
; #pragma unroll
;     for (int n = 0; n < 4; ++n) { const int rb = wc * 64 + n * 16 + fr; Bt[n] = *reinterpret_cast<const bf16x8*>(SB + rb * 64 + ((fq ^ ((rb >> 2) & 3)) * 16)); }
; #pragma unroll
;     for (int m = 0; m < 8; ++m) { const int ra = wr * 128 + m * 16 + fr; At[m] = *reinterpret_cast<const bf16x8*>(SA + ra * 64 + ((fq ^ ((ra >> 2) & 3)) * 16)); }
;     if (i + 3 < nk) stage(i + 3);
; #pragma unroll
;     for (int m = 0; m < 8; ++m)
; #pragma unroll
;       for (int n = 0; n < 4; ++n) acc[m][n] = __builtin_amdgcn_mfma_f32_16x16x32_bf16(Bt[n], At[m], acc[m][n], 0, 0, 0);
;   }
.Lgemm_p1_kloopv:
	s_add_i32 s6, s8, 0x18000
	s_and_b32 s6, s6, 0x18000
	s_add_i32 s9, s6, s7
	ds_read_b128 v[180:183], v215 offset:2048
	ds_read_b128 v[210:213], v215 offset:3072
	s_waitcnt lgkmcnt(2)
	v_mfma_f32_16x16x32_bf16 v[124:127], v[224:227], v[216:219], v[124:127]
	v_lshl_add_u64 v[206:207], v[184:185], 0, s[4:5]
	v_mfma_f32_16x16x32_bf16 v[120:123], v[224:227], v[220:223], v[120:123]
	s_mov_b32 m0, s9
	v_mfma_f32_16x16x32_bf16 v[116:119], v[224:227], v[232:235], v[116:119]
	s_add_i32 s9, s9, 0x2000
	v_mfma_f32_16x16x32_bf16 v[112:115], v[224:227], v[236:239], v[112:115]
	global_load_lds_dwordx4 v[206:207], off
	v_mfma_f32_16x16x32_bf16 v[108:111], v[228:231], v[216:219], v[108:111]
	v_mfma_f32_16x16x32_bf16 v[104:107], v[228:231], v[220:223], v[104:107]
	v_mfma_f32_16x16x32_bf16 v[100:103], v[228:231], v[232:235], v[100:103]
	v_mfma_f32_16x16x32_bf16 v[96:99], v[228:231], v[236:239], v[96:99]
	ds_read_b128 v[224:227], v215 offset:4096
	ds_read_b128 v[228:231], v215 offset:5120
	s_waitcnt lgkmcnt(2)
	v_mfma_f32_16x16x32_bf16 v[92:95], v[180:183], v[216:219], v[92:95]
	v_lshl_add_u64 v[206:207], v[186:187], 0, s[4:5]
	v_mfma_f32_16x16x32_bf16 v[88:91], v[180:183], v[220:223], v[88:91]
	s_mov_b32 m0, s9
	v_mfma_f32_16x16x32_bf16 v[84:87], v[180:183], v[232:235], v[84:87]
	s_add_i32 s9, s9, 0x2000
	v_mfma_f32_16x16x32_bf16 v[80:83], v[180:183], v[236:239], v[80:83]
	global_load_lds_dwordx4 v[206:207], off
	v_mfma_f32_16x16x32_bf16 v[76:79], v[210:213], v[216:219], v[76:79]
	v_mfma_f32_16x16x32_bf16 v[72:75], v[210:213], v[220:223], v[72:75]
	v_mfma_f32_16x16x32_bf16 v[68:71], v[210:213], v[232:235], v[68:71]
	v_mfma_f32_16x16x32_bf16 v[64:67], v[210:213], v[236:239], v[64:67]
	ds_read_b128 v[180:183], v215 offset:6144
	ds_read_b128 v[210:213], v215 offset:7168
	s_waitcnt lgkmcnt(2)
	v_mfma_f32_16x16x32_bf16 v[60:63], v[224:227], v[216:219], v[60:63]
	v_lshl_add_u64 v[206:207], v[172:173], 0, s[4:5]
	v_mfma_f32_16x16x32_bf16 v[56:59], v[224:227], v[220:223], v[56:59]
	s_mov_b32 m0, s9
	v_mfma_f32_16x16x32_bf16 v[52:55], v[224:227], v[232:235], v[52:55]
	s_add_i32 s9, s9, 0x2000
	v_mfma_f32_16x16x32_bf16 v[48:51], v[224:227], v[236:239], v[48:51]
	global_load_lds_dwordx4 v[206:207], off
	v_mfma_f32_16x16x32_bf16 v[44:47], v[228:231], v[216:219], v[44:47]
	v_mfma_f32_16x16x32_bf16 v[40:43], v[228:231], v[220:223], v[40:43]
	v_mfma_f32_16x16x32_bf16 v[36:39], v[228:231], v[232:235], v[36:39]
	v_mfma_f32_16x16x32_bf16 v[32:35], v[228:231], v[236:239], v[32:35]
	s_add_i32 s8, s8, 0x8000
	s_and_b32 s8, s8, 0x18000
	s_waitcnt vmcnt(7) lgkmcnt(0)
	s_barrier
	v_add3_u32 v252, v205, v147, s8
	v_add3_u32 v215, v205, v151, s8
	s_nop 0
	ds_read_b128 v[240:243], v252 offset:16384
	ds_read_b128 v[244:247], v252 offset:17408
	ds_read_b128 v[248:251], v252 offset:18432
	ds_read_b128 v[176:179], v252 offset:19456
	ds_read_b128 v[224:227], v215
	ds_read_b128 v[228:231], v215 offset:1024
	v_mfma_f32_16x16x32_bf16 v[28:31], v[180:183], v[216:219], v[28:31]
	v_lshl_add_u64 v[206:207], v[174:175], 0, s[4:5]
	v_mfma_f32_16x16x32_bf16 v[24:27], v[180:183], v[220:223], v[24:27]
	s_mov_b32 m0, s9
	v_mfma_f32_16x16x32_bf16 v[20:23], v[180:183], v[232:235], v[20:23]
	s_add_i32 s9, s9, 0x2000
	v_mfma_f32_16x16x32_bf16 v[16:19], v[180:183], v[236:239], v[16:19]
	global_load_lds_dwordx4 v[206:207], off
	v_mfma_f32_16x16x32_bf16 v[12:15], v[210:213], v[216:219], v[12:15]
	s_add_u32 s4, s4, 64
	v_mfma_f32_16x16x32_bf16 v[8:11], v[210:213], v[220:223], v[8:11]
	s_addc_u32 s5, s5, 0
	v_mfma_f32_16x16x32_bf16 v[4:7], v[210:213], v[232:235], v[4:7]
	v_mfma_f32_16x16x32_bf16 v[0:3], v[210:213], v[236:239], v[0:3]
	s_add_i32 s6, s8, 0x18000
	s_and_b32 s6, s6, 0x18000
	s_add_i32 s9, s6, s7
	ds_read_b128 v[180:183], v215 offset:2048
	ds_read_b128 v[210:213], v215 offset:3072
	s_waitcnt lgkmcnt(2)
	v_mfma_f32_16x16x32_bf16 v[124:127], v[224:227], v[240:243], v[124:127]
	v_lshl_add_u64 v[206:207], v[184:185], 0, s[4:5]
	v_mfma_f32_16x16x32_bf16 v[120:123], v[224:227], v[244:247], v[120:123]
	s_mov_b32 m0, s9
	v_mfma_f32_16x16x32_bf16 v[116:119], v[224:227], v[248:251], v[116:119]
	s_add_i32 s9, s9, 0x2000
	v_mfma_f32_16x16x32_bf16 v[112:115], v[224:227], v[176:179], v[112:115]
	global_load_lds_dwordx4 v[206:207], off
	v_mfma_f32_16x16x32_bf16 v[108:111], v[228:231], v[240:243], v[108:111]
	v_mfma_f32_16x16x32_bf16 v[104:107], v[228:231], v[244:247], v[104:107]
	v_mfma_f32_16x16x32_bf16 v[100:103], v[228:231], v[248:251], v[100:103]
	v_mfma_f32_16x16x32_bf16 v[96:99], v[228:231], v[176:179], v[96:99]
	ds_read_b128 v[224:227], v215 offset:4096
	ds_read_b128 v[228:231], v215 offset:5120
	s_waitcnt lgkmcnt(2)
	v_mfma_f32_16x16x32_bf16 v[92:95], v[180:183], v[240:243], v[92:95]
	v_lshl_add_u64 v[206:207], v[186:187], 0, s[4:5]
	v_mfma_f32_16x16x32_bf16 v[88:91], v[180:183], v[244:247], v[88:91]
	s_mov_b32 m0, s9
	v_mfma_f32_16x16x32_bf16 v[84:87], v[180:183], v[248:251], v[84:87]
	s_add_i32 s9, s9, 0x2000
	v_mfma_f32_16x16x32_bf16 v[80:83], v[180:183], v[176:179], v[80:83]
	global_load_lds_dwordx4 v[206:207], off
	v_mfma_f32_16x16x32_bf16 v[76:79], v[210:213], v[240:243], v[76:79]
	v_mfma_f32_16x16x32_bf16 v[72:75], v[210:213], v[244:247], v[72:75]
	v_mfma_f32_16x16x32_bf16 v[68:71], v[210:213], v[248:251], v[68:71]
	v_mfma_f32_16x16x32_bf16 v[64:67], v[210:213], v[176:179], v[64:67]
	ds_read_b128 v[180:183], v215 offset:6144
	ds_read_b128 v[210:213], v215 offset:7168
	s_waitcnt lgkmcnt(2)
	v_mfma_f32_16x16x32_bf16 v[60:63], v[224:227], v[240:243], v[60:63]
	v_lshl_add_u64 v[206:207], v[172:173], 0, s[4:5]
	v_mfma_f32_16x16x32_bf16 v[56:59], v[224:227], v[244:247], v[56:59]
	s_mov_b32 m0, s9
	v_mfma_f32_16x16x32_bf16 v[52:55], v[224:227], v[248:251], v[52:55]
	s_add_i32 s9, s9, 0x2000
	v_mfma_f32_16x16x32_bf16 v[48:51], v[224:227], v[176:179], v[48:51]
	global_load_lds_dwordx4 v[206:207], off
	v_mfma_f32_16x16x32_bf16 v[44:47], v[228:231], v[240:243], v[44:47]
	v_mfma_f32_16x16x32_bf16 v[40:43], v[228:231], v[244:247], v[40:43]
	v_mfma_f32_16x16x32_bf16 v[36:39], v[228:231], v[248:251], v[36:39]
	v_mfma_f32_16x16x32_bf16 v[32:35], v[228:231], v[176:179], v[32:35]
	s_add_i32 s8, s8, 0x8000
	s_and_b32 s8, s8, 0x18000
	s_waitcnt vmcnt(7) lgkmcnt(0)
	s_barrier
; template <class Epi>
; DI void gemm_tile256(const u16* __restrict__ Ag, long lda, const u16* __restrict__ Bg, long ldb, int nk, char* shm, Epi&& epi) {
;     ...
;   for (int i = 0; i < nk; ++i) {
;     if (i + 2 < nk) asm volatile("s_waitcnt vmcnt(8)" ::: "memory");
;     else if (i + 1 < nk) asm volatile("s_waitcnt vmcnt(4)" ::: "memory");
;     else asm volatile("s_waitcnt vmcnt(0)" ::: "memory");
;     __builtin_amdgcn_s_barrier();
;     const char* SA = shm + (i & 3) * 32768; const char* SB = SA + 16384;
;     bf16x8 At[8], Bt[4];
; #pragma unroll
;     for (int n = 0; n < 4; ++n) { const int rb = wc * 64 + n * 16 + fr; Bt[n] = *reinterpret_cast<const bf16x8*>(SB + rb * 64 + ((fq ^ ((rb >> 2) & 3)) * 16)); }
; #pragma unroll
;     for (int m = 0; m < 8; ++m) { const int ra = wr * 128 + m * 16 + fr; At[m] = *reinterpret_cast<const bf16x8*>(SA + ra * 64 + ((fq ^ ((ra >> 2) & 3)) * 16)); }
;     if (i + 3 < nk) stage(i + 3);
; #pragma unroll
;     for (int m = 0; m < 8; ++m)
; #pragma unroll
;       for (int n = 0; n < 4; ++n) acc[m][n] = __builtin_amdgcn_mfma_f32_16x16x32_bf16(Bt[n], At[m], acc[m][n], 0, 0, 0);
;   }
	v_add3_u32 v252, v205, v147, s8
	v_add3_u32 v215, v205, v151, s8
	s_nop 0
	ds_read_b128 v[216:219], v252 offset:16384
	ds_read_b128 v[220:223], v252 offset:17408
	ds_read_b128 v[232:235], v252 offset:18432
	ds_read_b128 v[236:239], v252 offset:19456
	ds_read_b128 v[224:227], v215
	ds_read_b128 v[228:231], v215 offset:1024
	v_mfma_f32_16x16x32_bf16 v[28:31], v[180:183], v[240:243], v[28:31]
	v_lshl_add_u64 v[206:207], v[174:175], 0, s[4:5]
	v_mfma_f32_16x16x32_bf16 v[24:27], v[180:183], v[244:247], v[24:27]
	s_mov_b32 m0, s9
	v_mfma_f32_16x16x32_bf16 v[20:23], v[180:183], v[248:251], v[20:23]
	s_add_i32 s9, s9, 0x2000
	v_mfma_f32_16x16x32_bf16 v[16:19], v[180:183], v[176:179], v[16:19]
	global_load_lds_dwordx4 v[206:207], off
	v_mfma_f32_16x16x32_bf16 v[12:15], v[210:213], v[240:243], v[12:15]
	s_add_u32 s4, s4, 64
	v_mfma_f32_16x16x32_bf16 v[8:11], v[210:213], v[244:247], v[8:11]
	s_addc_u32 s5, s5, 0
	v_mfma_f32_16x16x32_bf16 v[4:7], v[210:213], v[248:251], v[4:7]
	v_mfma_f32_16x16x32_bf16 v[0:3], v[210:213], v[176:179], v[0:3]
	s_cmpk_lg_i32 s4, 0x700
	s_cbranch_scc1 .Lgemm_p1_kloopv
	s_add_i32 s6, s8, 0x18000
	s_and_b32 s6, s6, 0x18000
	s_add_i32 s9, s6, s7
	ds_read_b128 v[180:183], v215 offset:2048
	ds_read_b128 v[210:213], v215 offset:3072
	s_waitcnt lgkmcnt(2)
	v_mfma_f32_16x16x32_bf16 v[124:127], v[224:227], v[216:219], v[124:127]
	v_lshl_add_u64 v[206:207], v[184:185], 0, s[4:5]
	v_mfma_f32_16x16x32_bf16 v[120:123], v[224:227], v[220:223], v[120:123]
	s_mov_b32 m0, s9
	v_mfma_f32_16x16x32_bf16 v[116:119], v[224:227], v[232:235], v[116:119]
	s_add_i32 s9, s9, 0x2000
	v_mfma_f32_16x16x32_bf16 v[112:115], v[224:227], v[236:239], v[112:115]
	global_load_lds_dwordx4 v[206:207], off
	v_mfma_f32_16x16x32_bf16 v[108:111], v[228:231], v[216:219], v[108:111]
	v_mfma_f32_16x16x32_bf16 v[104:107], v[228:231], v[220:223], v[104:107]
	v_mfma_f32_16x16x32_bf16 v[100:103], v[228:231], v[232:235], v[100:103]
	v_mfma_f32_16x16x32_bf16 v[96:99], v[228:231], v[236:239], v[96:99]
	ds_read_b128 v[224:227], v215 offset:4096
	ds_read_b128 v[228:231], v215 offset:5120
	s_waitcnt lgkmcnt(2)
	v_mfma_f32_16x16x32_bf16 v[92:95], v[180:183], v[216:219], v[92:95]
	v_lshl_add_u64 v[206:207], v[186:187], 0, s[4:5]
	v_mfma_f32_16x16x32_bf16 v[88:91], v[180:183], v[220:223], v[88:91]
	s_mov_b32 m0, s9
	v_mfma_f32_16x16x32_bf16 v[84:87], v[180:183], v[232:235], v[84:87]
	s_add_i32 s9, s9, 0x2000
	v_mfma_f32_16x16x32_bf16 v[80:83], v[180:183], v[236:239], v[80:83]
	global_load_lds_dwordx4 v[206:207], off
	v_mfma_f32_16x16x32_bf16 v[76:79], v[210:213], v[216:219], v[76:79]
	v_mfma_f32_16x16x32_bf16 v[72:75], v[210:213], v[220:223], v[72:75]
	v_mfma_f32_16x16x32_bf16 v[68:71], v[210:213], v[232:235], v[68:71]
	v_mfma_f32_16x16x32_bf16 v[64:67], v[210:213], v[236:239], v[64:67]
	ds_read_b128 v[180:183], v215 offset:6144
	ds_read_b128 v[210:213], v215 offset:7168
	s_waitcnt lgkmcnt(2)
	v_mfma_f32_16x16x32_bf16 v[60:63], v[224:227], v[216:219], v[60:63]
	v_lshl_add_u64 v[206:207], v[172:173], 0, s[4:5]
	v_mfma_f32_16x16x32_bf16 v[56:59], v[224:227], v[220:223], v[56:59]
	s_mov_b32 m0, s9
	v_mfma_f32_16x16x32_bf16 v[52:55], v[224:227], v[232:235], v[52:55]
	s_add_i32 s9, s9, 0x2000
	v_mfma_f32_16x16x32_bf16 v[48:51], v[224:227], v[236:239], v[48:51]
	global_load_lds_dwordx4 v[206:207], off
	v_mfma_f32_16x16x32_bf16 v[44:47], v[228:231], v[216:219], v[44:47]
	v_mfma_f32_16x16x32_bf16 v[40:43], v[228:231], v[220:223], v[40:43]
	v_mfma_f32_16x16x32_bf16 v[36:39], v[228:231], v[232:235], v[36:39]
	v_mfma_f32_16x16x32_bf16 v[32:35], v[228:231], v[236:239], v[32:35]
	s_add_i32 s8, s8, 0x8000
	s_and_b32 s8, s8, 0x18000
	s_waitcnt vmcnt(7) lgkmcnt(0)
	s_barrier
	v_add3_u32 v252, v205, v147, s8
	v_add3_u32 v215, v205, v151, s8
	s_nop 0
	ds_read_b128 v[240:243], v252 offset:16384
	ds_read_b128 v[244:247], v252 offset:17408
	ds_read_b128 v[248:251], v252 offset:18432
	ds_read_b128 v[176:179], v252 offset:19456
	ds_read_b128 v[224:227], v215
	ds_read_b128 v[228:231], v215 offset:1024
	v_mfma_f32_16x16x32_bf16 v[28:31], v[180:183], v[216:219], v[28:31]
	v_lshl_add_u64 v[206:207], v[174:175], 0, s[4:5]
	v_mfma_f32_16x16x32_bf16 v[24:27], v[180:183], v[220:223], v[24:27]
	s_mov_b32 m0, s9
	v_mfma_f32_16x16x32_bf16 v[20:23], v[180:183], v[232:235], v[20:23]
	s_add_i32 s9, s9, 0x2000
	v_mfma_f32_16x16x32_bf16 v[16:19], v[180:183], v[236:239], v[16:19]
	global_load_lds_dwordx4 v[206:207], off
	v_mfma_f32_16x16x32_bf16 v[12:15], v[210:213], v[216:219], v[12:15]
	s_add_u32 s4, s4, 64
	v_mfma_f32_16x16x32_bf16 v[8:11], v[210:213], v[220:223], v[8:11]
	s_addc_u32 s5, s5, 0
	v_mfma_f32_16x16x32_bf16 v[4:7], v[210:213], v[232:235], v[4:7]
	v_mfma_f32_16x16x32_bf16 v[0:3], v[210:213], v[236:239], v[0:3]
	ds_read_b128 v[180:183], v215 offset:2048
	ds_read_b128 v[210:213], v215 offset:3072
	s_waitcnt lgkmcnt(2)
	v_mfma_f32_16x16x32_bf16 v[124:127], v[224:227], v[240:243], v[124:127]
	v_mfma_f32_16x16x32_bf16 v[120:123], v[224:227], v[244:247], v[120:123]
	v_mfma_f32_16x16x32_bf16 v[116:119], v[224:227], v[248:251], v[116:119]
	v_mfma_f32_16x16x32_bf16 v[112:115], v[224:227], v[176:179], v[112:115]
	v_mfma_f32_16x16x32_bf16 v[108:111], v[228:231], v[240:243], v[108:111]
	v_mfma_f32_16x16x32_bf16 v[104:107], v[228:231], v[244:247], v[104:107]
	v_mfma_f32_16x16x32_bf16 v[100:103], v[228:231], v[248:251], v[100:103]
	v_mfma_f32_16x16x32_bf16 v[96:99], v[228:231], v[176:179], v[96:99]
	ds_read_b128 v[224:227], v215 offset:4096
	ds_read_b128 v[228:231], v215 offset:5120
	s_waitcnt lgkmcnt(2)
	v_mfma_f32_16x16x32_bf16 v[92:95], v[180:183], v[240:243], v[92:95]
	v_mfma_f32_16x16x32_bf16 v[88:91], v[180:183], v[244:247], v[88:91]
	v_mfma_f32_16x16x32_bf16 v[84:87], v[180:183], v[248:251], v[84:87]
	v_mfma_f32_16x16x32_bf16 v[80:83], v[180:183], v[176:179], v[80:83]
	v_mfma_f32_16x16x32_bf16 v[76:79], v[210:213], v[240:243], v[76:79]
	v_mfma_f32_16x16x32_bf16 v[72:75], v[210:213], v[244:247], v[72:75]
	v_mfma_f32_16x16x32_bf16 v[68:71], v[210:213], v[248:251], v[68:71]
	v_mfma_f32_16x16x32_bf16 v[64:67], v[210:213], v[176:179], v[64:67]
	ds_read_b128 v[180:183], v215 offset:6144
	ds_read_b128 v[210:213], v215 offset:7168
	s_waitcnt lgkmcnt(2)
	v_mfma_f32_16x16x32_bf16 v[60:63], v[224:227], v[240:243], v[60:63]
	v_mfma_f32_16x16x32_bf16 v[56:59], v[224:227], v[244:247], v[56:59]
	v_mfma_f32_16x16x32_bf16 v[52:55], v[224:227], v[248:251], v[52:55]
	v_mfma_f32_16x16x32_bf16 v[48:51], v[224:227], v[176:179], v[48:51]
	v_mfma_f32_16x16x32_bf16 v[44:47], v[228:231], v[240:243], v[44:47]
	v_mfma_f32_16x16x32_bf16 v[40:43], v[228:231], v[244:247], v[40:43]
	v_mfma_f32_16x16x32_bf16 v[36:39], v[228:231], v[248:251], v[36:39]
	v_mfma_f32_16x16x32_bf16 v[32:35], v[228:231], v[176:179], v[32:35]
	s_add_i32 s8, s8, 0x8000
	s_and_b32 s8, s8, 0x18000
	s_waitcnt vmcnt(4) lgkmcnt(0)
	s_barrier
; template <class Epi>
; DI void gemm_tile256(const u16* __restrict__ Ag, long lda, const u16* __restrict__ Bg, long ldb, int nk, char* shm, Epi&& epi) {
;     ...
;   for (int i = 0; i < nk; ++i) {
;     if (i + 2 < nk) asm volatile("s_waitcnt vmcnt(8)" ::: "memory");
;     else if (i + 1 < nk) asm volatile("s_waitcnt vmcnt(4)" ::: "memory");
;     else asm volatile("s_waitcnt vmcnt(0)" ::: "memory");
;     __builtin_amdgcn_s_barrier();
;     const char* SA = shm + (i & 3) * 32768; const char* SB = SA + 16384;
;     bf16x8 At[8], Bt[4];
; #pragma unroll
;     for (int n = 0; n < 4; ++n) { const int rb = wc * 64 + n * 16 + fr; Bt[n] = *reinterpret_cast<const bf16x8*>(SB + rb * 64 + ((fq ^ ((rb >> 2) & 3)) * 16)); }
; #pragma unroll
;     for (int m = 0; m < 8; ++m) { const int ra = wr * 128 + m * 16 + fr; At[m] = *reinterpret_cast<const bf16x8*>(SA + ra * 64 + ((fq ^ ((ra >> 2) & 3)) * 16)); }
;     if (i + 3 < nk) stage(i + 3);
; #pragma unroll
;     for (int m = 0; m < 8; ++m)
; #pragma unroll
;       for (int n = 0; n < 4; ++n) acc[m][n] = __builtin_amdgcn_mfma_f32_16x16x32_bf16(Bt[n], At[m], acc[m][n], 0, 0, 0);
;   }
;   __syncthreads();
; #pragma unroll
;   for (int m = 0; m < 8; ++m)
; #pragma unroll
;     for (int n = 0; n < 4; ++n) epi(wr * 128 + m * 16 + fr, wc * 64 + n * 16 + fq * 4, acc[m][n]);
	v_add3_u32 v252, v205, v147, s8
	v_add3_u32 v215, v205, v151, s8
	s_nop 0
	ds_read_b128 v[216:219], v252 offset:16384
	ds_read_b128 v[220:223], v252 offset:17408
	ds_read_b128 v[232:235], v252 offset:18432
	ds_read_b128 v[236:239], v252 offset:19456
	ds_read_b128 v[224:227], v215
	ds_read_b128 v[228:231], v215 offset:1024
	v_mfma_f32_16x16x32_bf16 v[28:31], v[180:183], v[240:243], v[28:31]
	v_mfma_f32_16x16x32_bf16 v[24:27], v[180:183], v[244:247], v[24:27]
	v_mfma_f32_16x16x32_bf16 v[20:23], v[180:183], v[248:251], v[20:23]
	v_mfma_f32_16x16x32_bf16 v[16:19], v[180:183], v[176:179], v[16:19]
	v_mfma_f32_16x16x32_bf16 v[12:15], v[210:213], v[240:243], v[12:15]
	v_mfma_f32_16x16x32_bf16 v[8:11], v[210:213], v[244:247], v[8:11]
	v_mfma_f32_16x16x32_bf16 v[4:7], v[210:213], v[248:251], v[4:7]
	v_mfma_f32_16x16x32_bf16 v[0:3], v[210:213], v[176:179], v[0:3]
	ds_read_b128 v[180:183], v215 offset:2048
	ds_read_b128 v[210:213], v215 offset:3072
	s_waitcnt lgkmcnt(2)
	v_mfma_f32_16x16x32_bf16 v[124:127], v[224:227], v[216:219], v[124:127]
	v_mfma_f32_16x16x32_bf16 v[120:123], v[224:227], v[220:223], v[120:123]
	v_mfma_f32_16x16x32_bf16 v[116:119], v[224:227], v[232:235], v[116:119]
	v_mfma_f32_16x16x32_bf16 v[112:115], v[224:227], v[236:239], v[112:115]
	v_mfma_f32_16x16x32_bf16 v[108:111], v[228:231], v[216:219], v[108:111]
	v_mfma_f32_16x16x32_bf16 v[104:107], v[228:231], v[220:223], v[104:107]
	v_mfma_f32_16x16x32_bf16 v[100:103], v[228:231], v[232:235], v[100:103]
	v_mfma_f32_16x16x32_bf16 v[96:99], v[228:231], v[236:239], v[96:99]
	ds_read_b128 v[224:227], v215 offset:4096
	ds_read_b128 v[228:231], v215 offset:5120
	s_waitcnt lgkmcnt(2)
	v_mfma_f32_16x16x32_bf16 v[92:95], v[180:183], v[216:219], v[92:95]
	v_mfma_f32_16x16x32_bf16 v[88:91], v[180:183], v[220:223], v[88:91]
	v_mfma_f32_16x16x32_bf16 v[84:87], v[180:183], v[232:235], v[84:87]
	v_mfma_f32_16x16x32_bf16 v[80:83], v[180:183], v[236:239], v[80:83]
	v_mfma_f32_16x16x32_bf16 v[76:79], v[210:213], v[216:219], v[76:79]
	v_mfma_f32_16x16x32_bf16 v[72:75], v[210:213], v[220:223], v[72:75]
	v_mfma_f32_16x16x32_bf16 v[68:71], v[210:213], v[232:235], v[68:71]
	v_mfma_f32_16x16x32_bf16 v[64:67], v[210:213], v[236:239], v[64:67]
	ds_read_b128 v[180:183], v215 offset:6144
	ds_read_b128 v[210:213], v215 offset:7168
	s_waitcnt lgkmcnt(2)
	v_mfma_f32_16x16x32_bf16 v[60:63], v[224:227], v[216:219], v[60:63]
	v_mfma_f32_16x16x32_bf16 v[56:59], v[224:227], v[220:223], v[56:59]
	v_mfma_f32_16x16x32_bf16 v[52:55], v[224:227], v[232:235], v[52:55]
	v_mfma_f32_16x16x32_bf16 v[48:51], v[224:227], v[236:239], v[48:51]
	v_mfma_f32_16x16x32_bf16 v[44:47], v[228:231], v[216:219], v[44:47]
	v_mfma_f32_16x16x32_bf16 v[40:43], v[228:231], v[220:223], v[40:43]
	v_mfma_f32_16x16x32_bf16 v[36:39], v[228:231], v[232:235], v[36:39]
	v_mfma_f32_16x16x32_bf16 v[32:35], v[228:231], v[236:239], v[32:35]
	s_add_i32 s8, s8, 0x8000
	s_and_b32 s8, s8, 0x18000
	s_waitcnt vmcnt(0) lgkmcnt(0)
	s_barrier
	v_add3_u32 v252, v205, v147, s8
	v_add3_u32 v215, v205, v151, s8
	s_nop 0
	ds_read_b128 v[240:243], v252 offset:16384
	ds_read_b128 v[244:247], v252 offset:17408
	ds_read_b128 v[248:251], v252 offset:18432
	ds_read_b128 v[176:179], v252 offset:19456
	ds_read_b128 v[224:227], v215
	ds_read_b128 v[228:231], v215 offset:1024
	v_mfma_f32_16x16x32_bf16 v[28:31], v[180:183], v[216:219], v[28:31]
	v_mfma_f32_16x16x32_bf16 v[24:27], v[180:183], v[220:223], v[24:27]
	v_mfma_f32_16x16x32_bf16 v[20:23], v[180:183], v[232:235], v[20:23]
	v_mfma_f32_16x16x32_bf16 v[16:19], v[180:183], v[236:239], v[16:19]
	v_mfma_f32_16x16x32_bf16 v[12:15], v[210:213], v[216:219], v[12:15]
	v_mfma_f32_16x16x32_bf16 v[8:11], v[210:213], v[220:223], v[8:11]
	v_mfma_f32_16x16x32_bf16 v[4:7], v[210:213], v[232:235], v[4:7]
	v_mfma_f32_16x16x32_bf16 v[0:3], v[210:213], v[236:239], v[0:3]
	ds_read_b128 v[180:183], v215 offset:2048
	ds_read_b128 v[210:213], v215 offset:3072
	s_waitcnt lgkmcnt(2)
	v_mfma_f32_16x16x32_bf16 v[124:127], v[224:227], v[240:243], v[124:127]
	v_mfma_f32_16x16x32_bf16 v[120:123], v[224:227], v[244:247], v[120:123]
	v_mfma_f32_16x16x32_bf16 v[116:119], v[224:227], v[248:251], v[116:119]
	v_mfma_f32_16x16x32_bf16 v[112:115], v[224:227], v[176:179], v[112:115]
	v_mfma_f32_16x16x32_bf16 v[108:111], v[228:231], v[240:243], v[108:111]
	v_mfma_f32_16x16x32_bf16 v[104:107], v[228:231], v[244:247], v[104:107]
	v_mfma_f32_16x16x32_bf16 v[100:103], v[228:231], v[248:251], v[100:103]
	v_mfma_f32_16x16x32_bf16 v[96:99], v[228:231], v[176:179], v[96:99]
	ds_read_b128 v[224:227], v215 offset:4096
	ds_read_b128 v[228:231], v215 offset:5120
	s_waitcnt lgkmcnt(2)
	v_mfma_f32_16x16x32_bf16 v[92:95], v[180:183], v[240:243], v[92:95]
	v_mfma_f32_16x16x32_bf16 v[88:91], v[180:183], v[244:247], v[88:91]
	v_mfma_f32_16x16x32_bf16 v[84:87], v[180:183], v[248:251], v[84:87]
	v_mfma_f32_16x16x32_bf16 v[80:83], v[180:183], v[176:179], v[80:83]
	v_mfma_f32_16x16x32_bf16 v[76:79], v[210:213], v[240:243], v[76:79]
	v_mfma_f32_16x16x32_bf16 v[72:75], v[210:213], v[244:247], v[72:75]
	v_mfma_f32_16x16x32_bf16 v[68:71], v[210:213], v[248:251], v[68:71]
	v_mfma_f32_16x16x32_bf16 v[64:67], v[210:213], v[176:179], v[64:67]
	ds_read_b128 v[180:183], v215 offset:6144
	ds_read_b128 v[210:213], v215 offset:7168
	s_waitcnt lgkmcnt(2)
	v_mfma_f32_16x16x32_bf16 v[60:63], v[224:227], v[240:243], v[60:63]
	v_mfma_f32_16x16x32_bf16 v[56:59], v[224:227], v[244:247], v[56:59]
	v_mfma_f32_16x16x32_bf16 v[52:55], v[224:227], v[248:251], v[52:55]
	v_mfma_f32_16x16x32_bf16 v[48:51], v[224:227], v[176:179], v[48:51]
	v_mfma_f32_16x16x32_bf16 v[44:47], v[228:231], v[240:243], v[44:47]
	v_mfma_f32_16x16x32_bf16 v[40:43], v[228:231], v[244:247], v[40:43]
	v_mfma_f32_16x16x32_bf16 v[36:39], v[228:231], v[248:251], v[36:39]
	v_mfma_f32_16x16x32_bf16 v[32:35], v[228:231], v[176:179], v[32:35]
	s_waitcnt lgkmcnt(0)
	v_mfma_f32_16x16x32_bf16 v[28:31], v[180:183], v[240:243], v[28:31]
	v_mfma_f32_16x16x32_bf16 v[24:27], v[180:183], v[244:247], v[24:27]
	v_mfma_f32_16x16x32_bf16 v[20:23], v[180:183], v[248:251], v[20:23]
	v_mfma_f32_16x16x32_bf16 v[16:19], v[180:183], v[176:179], v[16:19]
	v_mfma_f32_16x16x32_bf16 v[12:15], v[210:213], v[240:243], v[12:15]
	v_mfma_f32_16x16x32_bf16 v[8:11], v[210:213], v[244:247], v[8:11]
	v_mfma_f32_16x16x32_bf16 v[4:7], v[210:213], v[248:251], v[4:7]
	v_mfma_f32_16x16x32_bf16 v[0:3], v[210:213], v[176:179], v[0:3]
	s_nop 7
	s_nop 3
	s_waitcnt vmcnt(0) lgkmcnt(0)
	s_barrier
; DI u16 f2bf(float x) { return (u16)(pack2bf(x, 0.f) & 0xffffu); }
; template <class Epi>
; DI void gemm_tile256(const u16* __restrict__ Ag, long lda, const u16* __restrict__ Bg, long ldb, int nk, char* shm, Epi&& epi) {
;     ...
;   __syncthreads();
; #pragma unroll
;   for (int m = 0; m < 8; ++m)
; #pragma unroll
;     for (int n = 0; n < 4; ++n) epi(wr * 128 + m * 16 + fr, wc * 64 + n * 16 + fq * 4, acc[m][n]);
; DI void phase1(const Params& P, char* smem) {
;     ...
;         const int hd = c - 1536, b = r >> 13, l = r & 8191;
; #pragma unroll
;         for (int j = 0; j < 4; ++j) Vt[((long)(b * 512 + hd + j)) * 8192 + l] = f2bf(v[j]);
	v_and_b32_e32 v184, 15, v208
	v_lshrrev_b32_e32 v185, 4, v208
	v_lshrrev_b32_e32 v186, 6, v189
	v_lshlrev_b32_e32 v186, 14, v186
	v_lshrrev_b32_e32 v206, 1, v185
	v_and_b32_e32 v207, 1, v185
	v_lshl_add_u32 v215, v184, 8, v186
	v_lshl_add_u32 v215, v207, 3, v215
	v_or_b32_e32 v252, 0, v206
	v_xor_b32_e32 v252, v252, v184
	v_lshl_add_u32 v176, v252, 4, v215
	v_or_b32_e32 v252, 2, v206
	v_xor_b32_e32 v252, v252, v184
	v_lshl_add_u32 v177, v252, 4, v215
	v_or_b32_e32 v252, 4, v206
	v_xor_b32_e32 v252, v252, v184
	v_lshl_add_u32 v178, v252, 4, v215
	v_or_b32_e32 v252, 6, v206
	v_xor_b32_e32 v252, v252, v184
	v_lshl_add_u32 v179, v252, 4, v215
	v_or_b32_e32 v252, 8, v206
	v_xor_b32_e32 v252, v252, v184
	v_lshl_add_u32 v180, v252, 4, v215
	v_or_b32_e32 v252, 10, v206
	v_xor_b32_e32 v252, v252, v184
	v_lshl_add_u32 v181, v252, 4, v215
	v_or_b32_e32 v252, 12, v206
	v_xor_b32_e32 v252, v252, v184
	v_lshl_add_u32 v211, v252, 4, v215
	v_or_b32_e32 v252, 14, v206
	v_xor_b32_e32 v252, v252, v184
	v_lshl_add_u32 v242, v252, 4, v215
	v_add_u32_e32 v253, 0, v185
	v_xor_b32_e32 v252, v184, v253
	v_lshl_add_u32 v243, v253, 8, v186
	v_lshl_add_u32 v243, v252, 4, v243
	v_add_u32_e32 v253, 4, v185
	v_xor_b32_e32 v252, v184, v253
	v_lshl_add_u32 v212, v253, 8, v186
	v_lshl_add_u32 v212, v252, 4, v212
	v_add_u32_e32 v253, 8, v185
	v_xor_b32_e32 v252, v184, v253
	v_lshl_add_u32 v213, v253, 8, v186
	v_lshl_add_u32 v213, v252, 4, v213
	v_add_u32_e32 v253, 12, v185
	v_xor_b32_e32 v252, v184, v253
	v_lshl_add_u32 v187, v253, 8, v186
	v_lshl_add_u32 v187, v252, 4, v187
	v_bfe_u32 v252, v189, 6, 2
	v_lshl_add_u32 v252, v252, 6, v185
	s_lshr_b32 s36, s30, 13
	s_lshl_b32 s36, s36, 9
	s_and_b32 s37, s74, 1
	s_lshl_b32 s37, s37, 8
	s_add_i32 s36, s36, s37
	v_add_u32_e32 v252, s36, v252
	v_lshlrev_b32_e32 v182, 14, v252
	s_and_b32 s36, s30, 0x1fff
	v_lshl_add_u32 v252, v190, 7, s36
	v_lshl_add_u32 v182, v252, 1, v182
	v_lshl_add_u32 v182, v184, 4, v182
	v_mov_b32_e32 v183, 0
	v_lshl_add_u64 v[182:183], v[182:183], 0, s[62:63]
	s_mov_b32 s38, 0x10000
	s_mov_b32 s39, 0
	v_lshl_add_u64 v[240:241], v[182:183], 0, s[38:39]
	s_lshl_b32 s38, s38, 1
	v_cvt_pk_bf16_f32 v124, v124, v125
	v_cvt_pk_bf16_f32 v125, v126, v127
	ds_write_b64 v176, v[124:125] offset:0
	v_cvt_pk_bf16_f32 v120, v120, v121
	v_cvt_pk_bf16_f32 v121, v122, v123
	ds_write_b64 v176, v[120:121] offset:4096
	v_cvt_pk_bf16_f32 v116, v116, v117
	v_cvt_pk_bf16_f32 v117, v118, v119
	ds_write_b64 v176, v[116:117] offset:8192
	v_cvt_pk_bf16_f32 v112, v112, v113
	v_cvt_pk_bf16_f32 v113, v114, v115
	ds_write_b64 v176, v[112:113] offset:12288
	v_cvt_pk_bf16_f32 v108, v108, v109
	v_cvt_pk_bf16_f32 v109, v110, v111
	ds_write_b64 v177, v[108:109] offset:0
	v_cvt_pk_bf16_f32 v104, v104, v105
	v_cvt_pk_bf16_f32 v105, v106, v107
	ds_write_b64 v177, v[104:105] offset:4096
	v_cvt_pk_bf16_f32 v100, v100, v101
	v_cvt_pk_bf16_f32 v101, v102, v103
	ds_write_b64 v177, v[100:101] offset:8192
	v_cvt_pk_bf16_f32 v96, v96, v97
	v_cvt_pk_bf16_f32 v97, v98, v99
	ds_write_b64 v177, v[96:97] offset:12288
	v_cvt_pk_bf16_f32 v92, v92, v93
	v_cvt_pk_bf16_f32 v93, v94, v95
	ds_write_b64 v178, v[92:93] offset:0
	v_cvt_pk_bf16_f32 v88, v88, v89
	v_cvt_pk_bf16_f32 v89, v90, v91
	ds_write_b64 v178, v[88:89] offset:4096
	v_cvt_pk_bf16_f32 v84, v84, v85
	v_cvt_pk_bf16_f32 v85, v86, v87
	ds_write_b64 v178, v[84:85] offset:8192
	v_cvt_pk_bf16_f32 v80, v80, v81
	v_cvt_pk_bf16_f32 v81, v82, v83
	ds_write_b64 v178, v[80:81] offset:12288
	v_cvt_pk_bf16_f32 v76, v76, v77
	v_cvt_pk_bf16_f32 v77, v78, v79
	ds_write_b64 v179, v[76:77] offset:0
	v_cvt_pk_bf16_f32 v72, v72, v73
	v_cvt_pk_bf16_f32 v73, v74, v75
	ds_write_b64 v179, v[72:73] offset:4096
	v_cvt_pk_bf16_f32 v68, v68, v69
	v_cvt_pk_bf16_f32 v69, v70, v71
	ds_write_b64 v179, v[68:69] offset:8192
	v_cvt_pk_bf16_f32 v64, v64, v65
	v_cvt_pk_bf16_f32 v65, v66, v67
	ds_write_b64 v179, v[64:65] offset:12288
	v_cvt_pk_bf16_f32 v60, v60, v61
	v_cvt_pk_bf16_f32 v61, v62, v63
	ds_write_b64 v180, v[60:61] offset:0
	v_cvt_pk_bf16_f32 v56, v56, v57
	v_cvt_pk_bf16_f32 v57, v58, v59
	ds_write_b64 v180, v[56:57] offset:4096
	v_cvt_pk_bf16_f32 v52, v52, v53
	v_cvt_pk_bf16_f32 v53, v54, v55
	ds_write_b64 v180, v[52:53] offset:8192
	v_cvt_pk_bf16_f32 v48, v48, v49
	v_cvt_pk_bf16_f32 v49, v50, v51
	ds_write_b64 v180, v[48:49] offset:12288
	v_cvt_pk_bf16_f32 v44, v44, v45
	v_cvt_pk_bf16_f32 v45, v46, v47
	ds_write_b64 v181, v[44:45] offset:0
	v_cvt_pk_bf16_f32 v40, v40, v41
	v_cvt_pk_bf16_f32 v41, v42, v43
	ds_write_b64 v181, v[40:41] offset:4096
	v_cvt_pk_bf16_f32 v36, v36, v37
	v_cvt_pk_bf16_f32 v37, v38, v39
	ds_write_b64 v181, v[36:37] offset:8192
	v_cvt_pk_bf16_f32 v32, v32, v33
	v_cvt_pk_bf16_f32 v33, v34, v35
	ds_write_b64 v181, v[32:33] offset:12288
	v_cvt_pk_bf16_f32 v28, v28, v29
	v_cvt_pk_bf16_f32 v29, v30, v31
	ds_write_b64 v211, v[28:29] offset:0
	v_cvt_pk_bf16_f32 v24, v24, v25
	v_cvt_pk_bf16_f32 v25, v26, v27
	ds_write_b64 v211, v[24:25] offset:4096
	v_cvt_pk_bf16_f32 v20, v20, v21
	v_cvt_pk_bf16_f32 v21, v22, v23
	ds_write_b64 v211, v[20:21] offset:8192
	v_cvt_pk_bf16_f32 v16, v16, v17
	v_cvt_pk_bf16_f32 v17, v18, v19
	ds_write_b64 v211, v[16:17] offset:12288
	v_cvt_pk_bf16_f32 v12, v12, v13
	v_cvt_pk_bf16_f32 v13, v14, v15
	ds_write_b64 v242, v[12:13] offset:0
	v_cvt_pk_bf16_f32 v8, v8, v9
	v_cvt_pk_bf16_f32 v9, v10, v11
	ds_write_b64 v242, v[8:9] offset:4096
	v_cvt_pk_bf16_f32 v4, v4, v5
	v_cvt_pk_bf16_f32 v5, v6, v7
	ds_write_b64 v242, v[4:5] offset:8192
	v_cvt_pk_bf16_f32 v0, v0, v1
	v_cvt_pk_bf16_f32 v1, v2, v3
	ds_write_b64 v242, v[0:1] offset:12288
	s_waitcnt lgkmcnt(0)
; DI u16 f2bf(float x) { return (u16)(pack2bf(x, 0.f) & 0xffffu); }
; DI void phase1(const Params& P, char* smem) {
;     ...
;         const int hd = c - 1536, b = r >> 13, l = r & 8191;
; #pragma unroll
;         for (int j = 0; j < 4; ++j) Vt[((long)(b * 512 + hd + j)) * 8192 + l] = f2bf(v[j]);
	ds_read_b128 v[216:219], v243 offset:0
	ds_read_b128 v[220:223], v212 offset:0
	ds_read_b128 v[224:227], v213 offset:0
	ds_read_b128 v[228:231], v187 offset:0
	s_waitcnt lgkmcnt(3)
	global_store_dwordx4 v[182:183], v[216:219], off
	s_nop 0
	v_lshl_add_u64 v[182:183], v[182:183], 0, s[38:39]
	s_waitcnt lgkmcnt(2)
	global_store_dwordx4 v[240:241], v[220:223], off
	s_nop 0
	v_lshl_add_u64 v[240:241], v[240:241], 0, s[38:39]
	s_waitcnt lgkmcnt(1)
	global_store_dwordx4 v[182:183], v[224:227], off
	s_nop 0
	v_lshl_add_u64 v[182:183], v[182:183], 0, s[38:39]
	s_waitcnt lgkmcnt(0)
	global_store_dwordx4 v[240:241], v[228:231], off
	s_nop 0
	v_lshl_add_u64 v[240:241], v[240:241], 0, s[38:39]
	ds_read_b128 v[232:235], v243 offset:4096
	ds_read_b128 v[236:239], v212 offset:4096
	ds_read_b128 v[244:247], v213 offset:4096
	ds_read_b128 v[248:251], v187 offset:4096
	s_waitcnt lgkmcnt(3)
	global_store_dwordx4 v[182:183], v[232:235], off
	s_nop 0
	v_lshl_add_u64 v[182:183], v[182:183], 0, s[38:39]
	s_waitcnt lgkmcnt(2)
	global_store_dwordx4 v[240:241], v[236:239], off
	s_nop 0
	v_lshl_add_u64 v[240:241], v[240:241], 0, s[38:39]
	s_waitcnt lgkmcnt(1)
	global_store_dwordx4 v[182:183], v[244:247], off
	s_nop 0
	v_lshl_add_u64 v[182:183], v[182:183], 0, s[38:39]
	s_waitcnt lgkmcnt(0)
	global_store_dwordx4 v[240:241], v[248:251], off
	s_nop 0
	v_lshl_add_u64 v[240:241], v[240:241], 0, s[38:39]
	ds_read_b128 v[216:219], v243 offset:8192
	ds_read_b128 v[220:223], v212 offset:8192
	ds_read_b128 v[224:227], v213 offset:8192
	ds_read_b128 v[228:231], v187 offset:8192
	s_waitcnt lgkmcnt(3)
	global_store_dwordx4 v[182:183], v[216:219], off
	s_nop 0
	v_lshl_add_u64 v[182:183], v[182:183], 0, s[38:39]
	s_waitcnt lgkmcnt(2)
	global_store_dwordx4 v[240:241], v[220:223], off
	s_nop 0
	v_lshl_add_u64 v[240:241], v[240:241], 0, s[38:39]
	s_waitcnt lgkmcnt(1)
	global_store_dwordx4 v[182:183], v[224:227], off
	s_nop 0
	v_lshl_add_u64 v[182:183], v[182:183], 0, s[38:39]
	s_waitcnt lgkmcnt(0)
	global_store_dwordx4 v[240:241], v[228:231], off
	s_nop 0
	v_lshl_add_u64 v[240:241], v[240:241], 0, s[38:39]
	ds_read_b128 v[232:235], v243 offset:12288
	ds_read_b128 v[236:239], v212 offset:12288
	ds_read_b128 v[244:247], v213 offset:12288
	ds_read_b128 v[248:251], v187 offset:12288
	s_waitcnt lgkmcnt(3)
	global_store_dwordx4 v[182:183], v[232:235], off
	s_nop 0
	v_lshl_add_u64 v[182:183], v[182:183], 0, s[38:39]
	s_waitcnt lgkmcnt(2)
	global_store_dwordx4 v[240:241], v[236:239], off
	s_nop 0
	v_lshl_add_u64 v[240:241], v[240:241], 0, s[38:39]
	s_waitcnt lgkmcnt(1)
	global_store_dwordx4 v[182:183], v[244:247], off
	s_nop 0
	v_lshl_add_u64 v[182:183], v[182:183], 0, s[38:39]
	s_waitcnt lgkmcnt(0)
	global_store_dwordx4 v[240:241], v[248:251], off
	s_nop 0
	v_lshl_add_u64 v[240:241], v[240:241], 0, s[38:39]
	v_or_b32_e32 v212, 0x50, v153
	v_or_b32_e32 v213, 0x60, v153
	s_branch .LBB0_106

; template <class Epi>
; DI void gemm_tile256(const u16* __restrict__ Ag, long lda, const u16* __restrict__ Bg, long ldb, int nk, char* shm, Epi&& epi) {
;     ...
;   for (int i = 0; i < nk; ++i) {
;     if (i + 2 < nk) asm volatile("s_waitcnt vmcnt(8)" ::: "memory");
;     else if (i + 1 < nk) asm volatile("s_waitcnt vmcnt(4)" ::: "memory");
;     else asm volatile("s_waitcnt vmcnt(0)" ::: "memory");
;     __builtin_amdgcn_s_barrier();
;     const char* SA = shm + (i & 3) * 32768; const char* SB = SA + 16384;
;     bf16x8 At[8], Bt[4];
; #pragma unroll
;     for (int n = 0; n < 4; ++n) { const int rb = wc * 64 + n * 16 + fr; Bt[n] = *reinterpret_cast<const bf16x8*>(SB + rb * 64 + ((fq ^ ((rb >> 2) & 3)) * 16)); }
; #pragma unroll
;     for (int m = 0; m < 8; ++m) { const int ra = wr * 128 + m * 16 + fr; At[m] = *reinterpret_cast<const bf16x8*>(SA + ra * 64 + ((fq ^ ((ra >> 2) & 3)) * 16)); }
;     if (i + 3 < nk) stage(i + 3);
; #pragma unroll
;     for (int m = 0; m < 8; ++m)
; #pragma unroll
;       for (int n = 0; n < 4; ++n) acc[m][n] = __builtin_amdgcn_mfma_f32_16x16x32_bf16(Bt[n], At[m], acc[m][n], 0, 0, 0);
;   }
.Lgemm_p1_kloopn:
	s_add_i32 s6, s8, 0x18000
	s_and_b32 s6, s6, 0x18000
	s_add_i32 s9, s6, s7
	ds_read_b128 v[180:183], v215 offset:2048
	ds_read_b128 v[210:213], v215 offset:3072
	s_waitcnt lgkmcnt(2)
	v_mfma_f32_16x16x32_bf16 v[124:127], v[216:219], v[224:227], v[124:127]
	v_lshl_add_u64 v[206:207], v[184:185], 0, s[4:5]
	v_mfma_f32_16x16x32_bf16 v[120:123], v[220:223], v[224:227], v[120:123]
	s_mov_b32 m0, s9
	v_mfma_f32_16x16x32_bf16 v[116:119], v[232:235], v[224:227], v[116:119]
	s_add_i32 s9, s9, 0x2000
	v_mfma_f32_16x16x32_bf16 v[112:115], v[236:239], v[224:227], v[112:115]
	global_load_lds_dwordx4 v[206:207], off
	v_mfma_f32_16x16x32_bf16 v[108:111], v[216:219], v[228:231], v[108:111]
	v_mfma_f32_16x16x32_bf16 v[104:107], v[220:223], v[228:231], v[104:107]
	v_mfma_f32_16x16x32_bf16 v[100:103], v[232:235], v[228:231], v[100:103]
	v_mfma_f32_16x16x32_bf16 v[96:99], v[236:239], v[228:231], v[96:99]
	ds_read_b128 v[224:227], v215 offset:4096
	ds_read_b128 v[228:231], v215 offset:5120
	s_waitcnt lgkmcnt(2)
	v_mfma_f32_16x16x32_bf16 v[92:95], v[216:219], v[180:183], v[92:95]
	v_lshl_add_u64 v[206:207], v[186:187], 0, s[4:5]
	v_mfma_f32_16x16x32_bf16 v[88:91], v[220:223], v[180:183], v[88:91]
	s_mov_b32 m0, s9
	v_mfma_f32_16x16x32_bf16 v[84:87], v[232:235], v[180:183], v[84:87]
	s_add_i32 s9, s9, 0x2000
	v_mfma_f32_16x16x32_bf16 v[80:83], v[236:239], v[180:183], v[80:83]
	global_load_lds_dwordx4 v[206:207], off
	v_mfma_f32_16x16x32_bf16 v[76:79], v[216:219], v[210:213], v[76:79]
	v_mfma_f32_16x16x32_bf16 v[72:75], v[220:223], v[210:213], v[72:75]
	v_mfma_f32_16x16x32_bf16 v[68:71], v[232:235], v[210:213], v[68:71]
	v_mfma_f32_16x16x32_bf16 v[64:67], v[236:239], v[210:213], v[64:67]
	ds_read_b128 v[180:183], v215 offset:6144
	ds_read_b128 v[210:213], v215 offset:7168
	s_waitcnt lgkmcnt(2)
	v_mfma_f32_16x16x32_bf16 v[60:63], v[216:219], v[224:227], v[60:63]
	v_lshl_add_u64 v[206:207], v[172:173], 0, s[4:5]
	v_mfma_f32_16x16x32_bf16 v[56:59], v[220:223], v[224:227], v[56:59]
	s_mov_b32 m0, s9
	v_mfma_f32_16x16x32_bf16 v[52:55], v[232:235], v[224:227], v[52:55]
	s_add_i32 s9, s9, 0x2000
	v_mfma_f32_16x16x32_bf16 v[48:51], v[236:239], v[224:227], v[48:51]
	global_load_lds_dwordx4 v[206:207], off
	v_mfma_f32_16x16x32_bf16 v[44:47], v[216:219], v[228:231], v[44:47]
	v_mfma_f32_16x16x32_bf16 v[40:43], v[220:223], v[228:231], v[40:43]
	v_mfma_f32_16x16x32_bf16 v[36:39], v[232:235], v[228:231], v[36:39]
	v_mfma_f32_16x16x32_bf16 v[32:35], v[236:239], v[228:231], v[32:35]
	s_add_i32 s8, s8, 0x8000
	s_and_b32 s8, s8, 0x18000
	s_waitcnt vmcnt(7) lgkmcnt(0)
	s_barrier
	v_add3_u32 v252, v205, v147, s8
	v_add3_u32 v215, v205, v151, s8
	s_nop 0
	ds_read_b128 v[240:243], v252 offset:16384
	ds_read_b128 v[244:247], v252 offset:17408
	ds_read_b128 v[248:251], v252 offset:18432
	ds_read_b128 v[176:179], v252 offset:19456
	ds_read_b128 v[224:227], v215
	ds_read_b128 v[228:231], v215 offset:1024
	v_mfma_f32_16x16x32_bf16 v[28:31], v[216:219], v[180:183], v[28:31]
	v_lshl_add_u64 v[206:207], v[174:175], 0, s[4:5]
	v_mfma_f32_16x16x32_bf16 v[24:27], v[220:223], v[180:183], v[24:27]
	s_mov_b32 m0, s9
	v_mfma_f32_16x16x32_bf16 v[20:23], v[232:235], v[180:183], v[20:23]
	s_add_i32 s9, s9, 0x2000
	v_mfma_f32_16x16x32_bf16 v[16:19], v[236:239], v[180:183], v[16:19]
	global_load_lds_dwordx4 v[206:207], off
	v_mfma_f32_16x16x32_bf16 v[12:15], v[216:219], v[210:213], v[12:15]
	s_add_u32 s4, s4, 64
	v_mfma_f32_16x16x32_bf16 v[8:11], v[220:223], v[210:213], v[8:11]
	s_addc_u32 s5, s5, 0
	v_mfma_f32_16x16x32_bf16 v[4:7], v[232:235], v[210:213], v[4:7]
	v_mfma_f32_16x16x32_bf16 v[0:3], v[236:239], v[210:213], v[0:3]
	s_add_i32 s6, s8, 0x18000
	s_and_b32 s6, s6, 0x18000
	s_add_i32 s9, s6, s7
	ds_read_b128 v[180:183], v215 offset:2048
	ds_read_b128 v[210:213], v215 offset:3072
	s_waitcnt lgkmcnt(2)
	v_mfma_f32_16x16x32_bf16 v[124:127], v[240:243], v[224:227], v[124:127]
	v_lshl_add_u64 v[206:207], v[184:185], 0, s[4:5]
	v_mfma_f32_16x16x32_bf16 v[120:123], v[244:247], v[224:227], v[120:123]
	s_mov_b32 m0, s9
	v_mfma_f32_16x16x32_bf16 v[116:119], v[248:251], v[224:227], v[116:119]
	s_add_i32 s9, s9, 0x2000
	v_mfma_f32_16x16x32_bf16 v[112:115], v[176:179], v[224:227], v[112:115]
	global_load_lds_dwordx4 v[206:207], off
	v_mfma_f32_16x16x32_bf16 v[108:111], v[240:243], v[228:231], v[108:111]
	v_mfma_f32_16x16x32_bf16 v[104:107], v[244:247], v[228:231], v[104:107]
	v_mfma_f32_16x16x32_bf16 v[100:103], v[248:251], v[228:231], v[100:103]
	v_mfma_f32_16x16x32_bf16 v[96:99], v[176:179], v[228:231], v[96:99]
	ds_read_b128 v[224:227], v215 offset:4096
	ds_read_b128 v[228:231], v215 offset:5120
	s_waitcnt lgkmcnt(2)
	v_mfma_f32_16x16x32_bf16 v[92:95], v[240:243], v[180:183], v[92:95]
	v_lshl_add_u64 v[206:207], v[186:187], 0, s[4:5]
	v_mfma_f32_16x16x32_bf16 v[88:91], v[244:247], v[180:183], v[88:91]
	s_mov_b32 m0, s9
	v_mfma_f32_16x16x32_bf16 v[84:87], v[248:251], v[180:183], v[84:87]
	s_add_i32 s9, s9, 0x2000
	v_mfma_f32_16x16x32_bf16 v[80:83], v[176:179], v[180:183], v[80:83]
	global_load_lds_dwordx4 v[206:207], off
	v_mfma_f32_16x16x32_bf16 v[76:79], v[240:243], v[210:213], v[76:79]
	v_mfma_f32_16x16x32_bf16 v[72:75], v[244:247], v[210:213], v[72:75]
	v_mfma_f32_16x16x32_bf16 v[68:71], v[248:251], v[210:213], v[68:71]
	v_mfma_f32_16x16x32_bf16 v[64:67], v[176:179], v[210:213], v[64:67]
	ds_read_b128 v[180:183], v215 offset:6144
	ds_read_b128 v[210:213], v215 offset:7168
	s_waitcnt lgkmcnt(2)
	v_mfma_f32_16x16x32_bf16 v[60:63], v[240:243], v[224:227], v[60:63]
	v_lshl_add_u64 v[206:207], v[172:173], 0, s[4:5]
	v_mfma_f32_16x16x32_bf16 v[56:59], v[244:247], v[224:227], v[56:59]
	s_mov_b32 m0, s9
	v_mfma_f32_16x16x32_bf16 v[52:55], v[248:251], v[224:227], v[52:55]
	s_add_i32 s9, s9, 0x2000
	v_mfma_f32_16x16x32_bf16 v[48:51], v[176:179], v[224:227], v[48:51]
	global_load_lds_dwordx4 v[206:207], off
	v_mfma_f32_16x16x32_bf16 v[44:47], v[240:243], v[228:231], v[44:47]
	v_mfma_f32_16x16x32_bf16 v[40:43], v[244:247], v[228:231], v[40:43]
	v_mfma_f32_16x16x32_bf16 v[36:39], v[248:251], v[228:231], v[36:39]
	v_mfma_f32_16x16x32_bf16 v[32:35], v[176:179], v[228:231], v[32:35]
	s_add_i32 s8, s8, 0x8000
	s_and_b32 s8, s8, 0x18000
	s_waitcnt vmcnt(7) lgkmcnt(0)
	s_barrier
; template <class Epi>
; DI void gemm_tile256(const u16* __restrict__ Ag, long lda, const u16* __restrict__ Bg, long ldb, int nk, char* shm, Epi&& epi) {
;     ...
;   for (int i = 0; i < nk; ++i) {
;     if (i + 2 < nk) asm volatile("s_waitcnt vmcnt(8)" ::: "memory");
;     else if (i + 1 < nk) asm volatile("s_waitcnt vmcnt(4)" ::: "memory");
;     else asm volatile("s_waitcnt vmcnt(0)" ::: "memory");
;     __builtin_amdgcn_s_barrier();
;     const char* SA = shm + (i & 3) * 32768; const char* SB = SA + 16384;
;     bf16x8 At[8], Bt[4];
; #pragma unroll
;     for (int n = 0; n < 4; ++n) { const int rb = wc * 64 + n * 16 + fr; Bt[n] = *reinterpret_cast<const bf16x8*>(SB + rb * 64 + ((fq ^ ((rb >> 2) & 3)) * 16)); }
; #pragma unroll
;     for (int m = 0; m < 8; ++m) { const int ra = wr * 128 + m * 16 + fr; At[m] = *reinterpret_cast<const bf16x8*>(SA + ra * 64 + ((fq ^ ((ra >> 2) & 3)) * 16)); }
;     if (i + 3 < nk) stage(i + 3);
; #pragma unroll
;     for (int m = 0; m < 8; ++m)
; #pragma unroll
;       for (int n = 0; n < 4; ++n) acc[m][n] = __builtin_amdgcn_mfma_f32_16x16x32_bf16(Bt[n], At[m], acc[m][n], 0, 0, 0);
;   }
	v_add3_u32 v252, v205, v147, s8
	v_add3_u32 v215, v205, v151, s8
	s_nop 0
	ds_read_b128 v[216:219], v252 offset:16384
	ds_read_b128 v[220:223], v252 offset:17408
	ds_read_b128 v[232:235], v252 offset:18432
	ds_read_b128 v[236:239], v252 offset:19456
	ds_read_b128 v[224:227], v215
	ds_read_b128 v[228:231], v215 offset:1024
	v_mfma_f32_16x16x32_bf16 v[28:31], v[240:243], v[180:183], v[28:31]
	v_lshl_add_u64 v[206:207], v[174:175], 0, s[4:5]
	v_mfma_f32_16x16x32_bf16 v[24:27], v[244:247], v[180:183], v[24:27]
	s_mov_b32 m0, s9
	v_mfma_f32_16x16x32_bf16 v[20:23], v[248:251], v[180:183], v[20:23]
	s_add_i32 s9, s9, 0x2000
	v_mfma_f32_16x16x32_bf16 v[16:19], v[176:179], v[180:183], v[16:19]
	global_load_lds_dwordx4 v[206:207], off
	v_mfma_f32_16x16x32_bf16 v[12:15], v[240:243], v[210:213], v[12:15]
	s_add_u32 s4, s4, 64
	v_mfma_f32_16x16x32_bf16 v[8:11], v[244:247], v[210:213], v[8:11]
	s_addc_u32 s5, s5, 0
	v_mfma_f32_16x16x32_bf16 v[4:7], v[248:251], v[210:213], v[4:7]
	v_mfma_f32_16x16x32_bf16 v[0:3], v[176:179], v[210:213], v[0:3]
	s_cmpk_lg_i32 s4, 0x700
	s_cbranch_scc1 .Lgemm_p1_kloopn
	s_add_i32 s6, s8, 0x18000
	s_and_b32 s6, s6, 0x18000
	s_add_i32 s9, s6, s7
	ds_read_b128 v[180:183], v215 offset:2048
	ds_read_b128 v[210:213], v215 offset:3072
	s_waitcnt lgkmcnt(2)
	v_mfma_f32_16x16x32_bf16 v[124:127], v[216:219], v[224:227], v[124:127]
	v_lshl_add_u64 v[206:207], v[184:185], 0, s[4:5]
	v_mfma_f32_16x16x32_bf16 v[120:123], v[220:223], v[224:227], v[120:123]
	s_mov_b32 m0, s9
	v_mfma_f32_16x16x32_bf16 v[116:119], v[232:235], v[224:227], v[116:119]
	s_add_i32 s9, s9, 0x2000
	v_mfma_f32_16x16x32_bf16 v[112:115], v[236:239], v[224:227], v[112:115]
	global_load_lds_dwordx4 v[206:207], off
	v_mfma_f32_16x16x32_bf16 v[108:111], v[216:219], v[228:231], v[108:111]
	v_mfma_f32_16x16x32_bf16 v[104:107], v[220:223], v[228:231], v[104:107]
	v_mfma_f32_16x16x32_bf16 v[100:103], v[232:235], v[228:231], v[100:103]
	v_mfma_f32_16x16x32_bf16 v[96:99], v[236:239], v[228:231], v[96:99]
	ds_read_b128 v[224:227], v215 offset:4096
	ds_read_b128 v[228:231], v215 offset:5120
	s_waitcnt lgkmcnt(2)
	v_mfma_f32_16x16x32_bf16 v[92:95], v[216:219], v[180:183], v[92:95]
	v_lshl_add_u64 v[206:207], v[186:187], 0, s[4:5]
	v_mfma_f32_16x16x32_bf16 v[88:91], v[220:223], v[180:183], v[88:91]
	s_mov_b32 m0, s9
	v_mfma_f32_16x16x32_bf16 v[84:87], v[232:235], v[180:183], v[84:87]
	s_add_i32 s9, s9, 0x2000
	v_mfma_f32_16x16x32_bf16 v[80:83], v[236:239], v[180:183], v[80:83]
	global_load_lds_dwordx4 v[206:207], off
	v_mfma_f32_16x16x32_bf16 v[76:79], v[216:219], v[210:213], v[76:79]
	v_mfma_f32_16x16x32_bf16 v[72:75], v[220:223], v[210:213], v[72:75]
	v_mfma_f32_16x16x32_bf16 v[68:71], v[232:235], v[210:213], v[68:71]
	v_mfma_f32_16x16x32_bf16 v[64:67], v[236:239], v[210:213], v[64:67]
	ds_read_b128 v[180:183], v215 offset:6144
	ds_read_b128 v[210:213], v215 offset:7168
	s_waitcnt lgkmcnt(2)
	v_mfma_f32_16x16x32_bf16 v[60:63], v[216:219], v[224:227], v[60:63]
	v_lshl_add_u64 v[206:207], v[172:173], 0, s[4:5]
	v_mfma_f32_16x16x32_bf16 v[56:59], v[220:223], v[224:227], v[56:59]
	s_mov_b32 m0, s9
	v_mfma_f32_16x16x32_bf16 v[52:55], v[232:235], v[224:227], v[52:55]
	s_add_i32 s9, s9, 0x2000
	v_mfma_f32_16x16x32_bf16 v[48:51], v[236:239], v[224:227], v[48:51]
	global_load_lds_dwordx4 v[206:207], off
	v_mfma_f32_16x16x32_bf16 v[44:47], v[216:219], v[228:231], v[44:47]
	v_mfma_f32_16x16x32_bf16 v[40:43], v[220:223], v[228:231], v[40:43]
	v_mfma_f32_16x16x32_bf16 v[36:39], v[232:235], v[228:231], v[36:39]
	v_mfma_f32_16x16x32_bf16 v[32:35], v[236:239], v[228:231], v[32:35]
	s_add_i32 s8, s8, 0x8000
	s_and_b32 s8, s8, 0x18000
	s_waitcnt vmcnt(7) lgkmcnt(0)
	s_barrier
	v_add3_u32 v252, v205, v147, s8
	v_add3_u32 v215, v205, v151, s8
	s_nop 0
	ds_read_b128 v[240:243], v252 offset:16384
	ds_read_b128 v[244:247], v252 offset:17408
	ds_read_b128 v[248:251], v252 offset:18432
	ds_read_b128 v[176:179], v252 offset:19456
	ds_read_b128 v[224:227], v215
	ds_read_b128 v[228:231], v215 offset:1024
	v_mfma_f32_16x16x32_bf16 v[28:31], v[216:219], v[180:183], v[28:31]
	v_lshl_add_u64 v[206:207], v[174:175], 0, s[4:5]
	v_mfma_f32_16x16x32_bf16 v[24:27], v[220:223], v[180:183], v[24:27]
	s_mov_b32 m0, s9
	v_mfma_f32_16x16x32_bf16 v[20:23], v[232:235], v[180:183], v[20:23]
	s_add_i32 s9, s9, 0x2000
	v_mfma_f32_16x16x32_bf16 v[16:19], v[236:239], v[180:183], v[16:19]
	global_load_lds_dwordx4 v[206:207], off
	v_mfma_f32_16x16x32_bf16 v[12:15], v[216:219], v[210:213], v[12:15]
	s_add_u32 s4, s4, 64
	v_mfma_f32_16x16x32_bf16 v[8:11], v[220:223], v[210:213], v[8:11]
	s_addc_u32 s5, s5, 0
	v_mfma_f32_16x16x32_bf16 v[4:7], v[232:235], v[210:213], v[4:7]
	v_mfma_f32_16x16x32_bf16 v[0:3], v[236:239], v[210:213], v[0:3]
	ds_read_b128 v[180:183], v215 offset:2048
	ds_read_b128 v[210:213], v215 offset:3072
	s_waitcnt lgkmcnt(2)
	v_mfma_f32_16x16x32_bf16 v[124:127], v[240:243], v[224:227], v[124:127]
	v_mfma_f32_16x16x32_bf16 v[120:123], v[244:247], v[224:227], v[120:123]
	v_mfma_f32_16x16x32_bf16 v[116:119], v[248:251], v[224:227], v[116:119]
	v_mfma_f32_16x16x32_bf16 v[112:115], v[176:179], v[224:227], v[112:115]
	v_mfma_f32_16x16x32_bf16 v[108:111], v[240:243], v[228:231], v[108:111]
	v_mfma_f32_16x16x32_bf16 v[104:107], v[244:247], v[228:231], v[104:107]
	v_mfma_f32_16x16x32_bf16 v[100:103], v[248:251], v[228:231], v[100:103]
	v_mfma_f32_16x16x32_bf16 v[96:99], v[176:179], v[228:231], v[96:99]
	ds_read_b128 v[224:227], v215 offset:4096
	ds_read_b128 v[228:231], v215 offset:5120
	s_waitcnt lgkmcnt(2)
	v_mfma_f32_16x16x32_bf16 v[92:95], v[240:243], v[180:183], v[92:95]
	v_mfma_f32_16x16x32_bf16 v[88:91], v[244:247], v[180:183], v[88:91]
	v_mfma_f32_16x16x32_bf16 v[84:87], v[248:251], v[180:183], v[84:87]
	v_mfma_f32_16x16x32_bf16 v[80:83], v[176:179], v[180:183], v[80:83]
	v_mfma_f32_16x16x32_bf16 v[76:79], v[240:243], v[210:213], v[76:79]
	v_mfma_f32_16x16x32_bf16 v[72:75], v[244:247], v[210:213], v[72:75]
	v_mfma_f32_16x16x32_bf16 v[68:71], v[248:251], v[210:213], v[68:71]
	v_mfma_f32_16x16x32_bf16 v[64:67], v[176:179], v[210:213], v[64:67]
	ds_read_b128 v[180:183], v215 offset:6144
	ds_read_b128 v[210:213], v215 offset:7168
	s_waitcnt lgkmcnt(2)
	v_mfma_f32_16x16x32_bf16 v[60:63], v[240:243], v[224:227], v[60:63]
	v_mfma_f32_16x16x32_bf16 v[56:59], v[244:247], v[224:227], v[56:59]
	v_mfma_f32_16x16x32_bf16 v[52:55], v[248:251], v[224:227], v[52:55]
	v_mfma_f32_16x16x32_bf16 v[48:51], v[176:179], v[224:227], v[48:51]
	v_mfma_f32_16x16x32_bf16 v[44:47], v[240:243], v[228:231], v[44:47]
	v_mfma_f32_16x16x32_bf16 v[40:43], v[244:247], v[228:231], v[40:43]
	v_mfma_f32_16x16x32_bf16 v[36:39], v[248:251], v[228:231], v[36:39]
	v_mfma_f32_16x16x32_bf16 v[32:35], v[176:179], v[228:231], v[32:35]
	s_add_i32 s8, s8, 0x8000
	s_and_b32 s8, s8, 0x18000
	s_waitcnt vmcnt(4) lgkmcnt(0)
	s_barrier
; template <class Epi>
; DI void gemm_tile256(const u16* __restrict__ Ag, long lda, const u16* __restrict__ Bg, long ldb, int nk, char* shm, Epi&& epi) {
;     ...
;   for (int i = 0; i < nk; ++i) {
;     if (i + 2 < nk) asm volatile("s_waitcnt vmcnt(8)" ::: "memory");
;     else if (i + 1 < nk) asm volatile("s_waitcnt vmcnt(4)" ::: "memory");
;     else asm volatile("s_waitcnt vmcnt(0)" ::: "memory");
;     __builtin_amdgcn_s_barrier();
;     const char* SA = shm + (i & 3) * 32768; const char* SB = SA + 16384;
;     bf16x8 At[8], Bt[4];
; #pragma unroll
;     for (int n = 0; n < 4; ++n) { const int rb = wc * 64 + n * 16 + fr; Bt[n] = *reinterpret_cast<const bf16x8*>(SB + rb * 64 + ((fq ^ ((rb >> 2) & 3)) * 16)); }
; #pragma unroll
;     for (int m = 0; m < 8; ++m) { const int ra = wr * 128 + m * 16 + fr; At[m] = *reinterpret_cast<const bf16x8*>(SA + ra * 64 + ((fq ^ ((ra >> 2) & 3)) * 16)); }
;     if (i + 3 < nk) stage(i + 3);
; #pragma unroll
;     for (int m = 0; m < 8; ++m)
; #pragma unroll
;       for (int n = 0; n < 4; ++n) acc[m][n] = __builtin_amdgcn_mfma_f32_16x16x32_bf16(Bt[n], At[m], acc[m][n], 0, 0, 0);
;   }
;   __syncthreads();
; #pragma unroll
;   for (int m = 0; m < 8; ++m)
; #pragma unroll
;     for (int n = 0; n < 4; ++n) epi(wr * 128 + m * 16 + fr, wc * 64 + n * 16 + fq * 4, acc[m][n]);
; DI void phase1(const Params& P, char* smem) {
;     ...
;       if (bcol < 512) {
;         const int g = c >> 4, hp = c & 15, m = r >> 6, j = r & 63;
;         *reinterpret_cast<uint2*>(UG + ((long)g * 512 + m) * UGLD + j * 16 + hp) = pk;
;       } else if (bcol < 1024) {
;         *reinterpret_cast<uint2*>(Qb + (long)r * 512 + (c - 512)) = pk;
	v_add3_u32 v252, v205, v147, s8
	v_add3_u32 v215, v205, v151, s8
	s_nop 0
	ds_read_b128 v[216:219], v252 offset:16384
	ds_read_b128 v[220:223], v252 offset:17408
	ds_read_b128 v[232:235], v252 offset:18432
	ds_read_b128 v[236:239], v252 offset:19456
	ds_read_b128 v[224:227], v215
	ds_read_b128 v[228:231], v215 offset:1024
	v_mfma_f32_16x16x32_bf16 v[28:31], v[240:243], v[180:183], v[28:31]
	v_mfma_f32_16x16x32_bf16 v[24:27], v[244:247], v[180:183], v[24:27]
	v_mfma_f32_16x16x32_bf16 v[20:23], v[248:251], v[180:183], v[20:23]
	v_mfma_f32_16x16x32_bf16 v[16:19], v[176:179], v[180:183], v[16:19]
	v_mfma_f32_16x16x32_bf16 v[12:15], v[240:243], v[210:213], v[12:15]
	v_mfma_f32_16x16x32_bf16 v[8:11], v[244:247], v[210:213], v[8:11]
	v_mfma_f32_16x16x32_bf16 v[4:7], v[248:251], v[210:213], v[4:7]
	v_mfma_f32_16x16x32_bf16 v[0:3], v[176:179], v[210:213], v[0:3]
	ds_read_b128 v[180:183], v215 offset:2048
	ds_read_b128 v[210:213], v215 offset:3072
	s_waitcnt lgkmcnt(2)
	v_mfma_f32_16x16x32_bf16 v[124:127], v[216:219], v[224:227], v[124:127]
	v_mfma_f32_16x16x32_bf16 v[120:123], v[220:223], v[224:227], v[120:123]
	v_mfma_f32_16x16x32_bf16 v[116:119], v[232:235], v[224:227], v[116:119]
	v_mfma_f32_16x16x32_bf16 v[112:115], v[236:239], v[224:227], v[112:115]
	v_mfma_f32_16x16x32_bf16 v[108:111], v[216:219], v[228:231], v[108:111]
	v_mfma_f32_16x16x32_bf16 v[104:107], v[220:223], v[228:231], v[104:107]
	v_mfma_f32_16x16x32_bf16 v[100:103], v[232:235], v[228:231], v[100:103]
	v_mfma_f32_16x16x32_bf16 v[96:99], v[236:239], v[228:231], v[96:99]
	ds_read_b128 v[224:227], v215 offset:4096
	ds_read_b128 v[228:231], v215 offset:5120
	s_waitcnt lgkmcnt(2)
	v_mfma_f32_16x16x32_bf16 v[92:95], v[216:219], v[180:183], v[92:95]
	v_mfma_f32_16x16x32_bf16 v[88:91], v[220:223], v[180:183], v[88:91]
	v_mfma_f32_16x16x32_bf16 v[84:87], v[232:235], v[180:183], v[84:87]
	v_mfma_f32_16x16x32_bf16 v[80:83], v[236:239], v[180:183], v[80:83]
	v_mfma_f32_16x16x32_bf16 v[76:79], v[216:219], v[210:213], v[76:79]
	v_mfma_f32_16x16x32_bf16 v[72:75], v[220:223], v[210:213], v[72:75]
	v_mfma_f32_16x16x32_bf16 v[68:71], v[232:235], v[210:213], v[68:71]
	v_mfma_f32_16x16x32_bf16 v[64:67], v[236:239], v[210:213], v[64:67]
	ds_read_b128 v[180:183], v215 offset:6144
	ds_read_b128 v[210:213], v215 offset:7168
	s_waitcnt lgkmcnt(2)
	v_mfma_f32_16x16x32_bf16 v[60:63], v[216:219], v[224:227], v[60:63]
	v_mfma_f32_16x16x32_bf16 v[56:59], v[220:223], v[224:227], v[56:59]
	v_mfma_f32_16x16x32_bf16 v[52:55], v[232:235], v[224:227], v[52:55]
	v_mfma_f32_16x16x32_bf16 v[48:51], v[236:239], v[224:227], v[48:51]
	v_mfma_f32_16x16x32_bf16 v[44:47], v[216:219], v[228:231], v[44:47]
	v_mfma_f32_16x16x32_bf16 v[40:43], v[220:223], v[228:231], v[40:43]
	v_mfma_f32_16x16x32_bf16 v[36:39], v[232:235], v[228:231], v[36:39]
	v_mfma_f32_16x16x32_bf16 v[32:35], v[236:239], v[228:231], v[32:35]
	s_add_i32 s8, s8, 0x8000
	s_and_b32 s8, s8, 0x18000
	s_waitcnt vmcnt(0) lgkmcnt(0)
	s_barrier
	v_add3_u32 v252, v205, v147, s8
	v_add3_u32 v215, v205, v151, s8
	s_nop 0
	ds_read_b128 v[240:243], v252 offset:16384
	ds_read_b128 v[244:247], v252 offset:17408
	ds_read_b128 v[248:251], v252 offset:18432
	ds_read_b128 v[176:179], v252 offset:19456
	ds_read_b128 v[224:227], v215
	ds_read_b128 v[228:231], v215 offset:1024
	v_mfma_f32_16x16x32_bf16 v[28:31], v[216:219], v[180:183], v[28:31]
	v_mfma_f32_16x16x32_bf16 v[24:27], v[220:223], v[180:183], v[24:27]
	v_mfma_f32_16x16x32_bf16 v[20:23], v[232:235], v[180:183], v[20:23]
	v_mfma_f32_16x16x32_bf16 v[16:19], v[236:239], v[180:183], v[16:19]
	v_mfma_f32_16x16x32_bf16 v[12:15], v[216:219], v[210:213], v[12:15]
	v_mfma_f32_16x16x32_bf16 v[8:11], v[220:223], v[210:213], v[8:11]
	v_mfma_f32_16x16x32_bf16 v[4:7], v[232:235], v[210:213], v[4:7]
	v_mfma_f32_16x16x32_bf16 v[0:3], v[236:239], v[210:213], v[0:3]
	ds_read_b128 v[180:183], v215 offset:2048
	ds_read_b128 v[210:213], v215 offset:3072
	s_waitcnt lgkmcnt(2)
	v_mfma_f32_16x16x32_bf16 v[124:127], v[240:243], v[224:227], v[124:127]
	v_mfma_f32_16x16x32_bf16 v[120:123], v[244:247], v[224:227], v[120:123]
	v_mfma_f32_16x16x32_bf16 v[116:119], v[248:251], v[224:227], v[116:119]
	v_mfma_f32_16x16x32_bf16 v[112:115], v[176:179], v[224:227], v[112:115]
	v_mfma_f32_16x16x32_bf16 v[108:111], v[240:243], v[228:231], v[108:111]
	v_mfma_f32_16x16x32_bf16 v[104:107], v[244:247], v[228:231], v[104:107]
	v_mfma_f32_16x16x32_bf16 v[100:103], v[248:251], v[228:231], v[100:103]
	v_mfma_f32_16x16x32_bf16 v[96:99], v[176:179], v[228:231], v[96:99]
	ds_read_b128 v[224:227], v215 offset:4096
	ds_read_b128 v[228:231], v215 offset:5120
	s_waitcnt lgkmcnt(2)
	v_mfma_f32_16x16x32_bf16 v[92:95], v[240:243], v[180:183], v[92:95]
	v_mfma_f32_16x16x32_bf16 v[88:91], v[244:247], v[180:183], v[88:91]
	v_mfma_f32_16x16x32_bf16 v[84:87], v[248:251], v[180:183], v[84:87]
	v_mfma_f32_16x16x32_bf16 v[80:83], v[176:179], v[180:183], v[80:83]
	v_mfma_f32_16x16x32_bf16 v[76:79], v[240:243], v[210:213], v[76:79]
	v_mfma_f32_16x16x32_bf16 v[72:75], v[244:247], v[210:213], v[72:75]
	v_mfma_f32_16x16x32_bf16 v[68:71], v[248:251], v[210:213], v[68:71]
	v_mfma_f32_16x16x32_bf16 v[64:67], v[176:179], v[210:213], v[64:67]
	ds_read_b128 v[180:183], v215 offset:6144
	ds_read_b128 v[210:213], v215 offset:7168
	s_waitcnt lgkmcnt(2)
	v_mfma_f32_16x16x32_bf16 v[60:63], v[240:243], v[224:227], v[60:63]
	v_mfma_f32_16x16x32_bf16 v[56:59], v[244:247], v[224:227], v[56:59]
	v_mfma_f32_16x16x32_bf16 v[52:55], v[248:251], v[224:227], v[52:55]
	v_mfma_f32_16x16x32_bf16 v[48:51], v[176:179], v[224:227], v[48:51]
	v_mfma_f32_16x16x32_bf16 v[44:47], v[240:243], v[228:231], v[44:47]
	v_mfma_f32_16x16x32_bf16 v[40:43], v[244:247], v[228:231], v[40:43]
	v_mfma_f32_16x16x32_bf16 v[36:39], v[248:251], v[228:231], v[36:39]
	v_mfma_f32_16x16x32_bf16 v[32:35], v[176:179], v[228:231], v[32:35]
	s_waitcnt lgkmcnt(0)
	v_mfma_f32_16x16x32_bf16 v[28:31], v[240:243], v[180:183], v[28:31]
	v_mfma_f32_16x16x32_bf16 v[24:27], v[244:247], v[180:183], v[24:27]
	v_mfma_f32_16x16x32_bf16 v[20:23], v[248:251], v[180:183], v[20:23]
	v_mfma_f32_16x16x32_bf16 v[16:19], v[176:179], v[180:183], v[16:19]
	v_mfma_f32_16x16x32_bf16 v[12:15], v[240:243], v[210:213], v[12:15]
	v_mfma_f32_16x16x32_bf16 v[8:11], v[244:247], v[210:213], v[8:11]
	v_mfma_f32_16x16x32_bf16 v[4:7], v[248:251], v[210:213], v[4:7]
	v_mfma_f32_16x16x32_bf16 v[0:3], v[176:179], v[210:213], v[0:3]
	s_nop 7
	s_nop 3
	s_and_b64 vcc, exec, s[10:11]
	s_cbranch_vccz .Lgemm_p1_u
; DI unsigned pack2bf(float a, float b) { const f2_t v = {a, b}; return __builtin_bit_cast(unsigned, __builtin_convertvector(v, bf2_t)); }
; template <class Epi>
; DI void gemm_tile256(const u16* __restrict__ Ag, long lda, const u16* __restrict__ Bg, long ldb, int nk, char* shm, Epi&& epi) {
;     ...
;   __syncthreads();
; #pragma unroll
;   for (int m = 0; m < 8; ++m)
; #pragma unroll
;     for (int n = 0; n < 4; ++n) epi(wr * 128 + m * 16 + fr, wc * 64 + n * 16 + fq * 4, acc[m][n]);
; DI void phase1(const Params& P, char* smem) {
;     ...
;       const int r = brow + row, c = bcol + col0;
;       const uint2 pk = make_uint2(pack2bf(v[0], v[1]), pack2bf(v[2], v[3]));
;       if (bcol < 512) {
;         const int g = c >> 4, hp = c & 15, m = r >> 6, j = r & 63;
;         *reinterpret_cast<uint2*>(UG + ((long)g * 512 + m) * UGLD + j * 16 + hp) = pk;
;       } else if (bcol < 1024) {
;         *reinterpret_cast<uint2*>(Qb + (long)r * 512 + (c - 512)) = pk;
;       } else if (bcol < 1536) {
;         *reinterpret_cast<uint2*>(Kb + (long)r * 512 + (c - 1024)) = pk;
	s_waitcnt vmcnt(0) lgkmcnt(0)
	s_barrier
	v_and_b32_e32 v184, 15, v208
	v_lshrrev_b32_e32 v185, 4, v208
	v_lshrrev_b32_e32 v186, 6, v189
	v_lshlrev_b32_e32 v186, 14, v186
	v_and_b32_e32 v187, 7, v184
	v_lshrrev_b32_e32 v206, 1, v185
	v_and_b32_e32 v207, 1, v185
	v_lshl_add_u32 v215, v184, 7, v186
	v_lshl_add_u32 v215, v207, 3, v215
	v_or_b32_e32 v252, 0, v206
	v_xor_b32_e32 v252, v252, v187
	v_lshl_add_u32 v176, v252, 4, v215
	v_or_b32_e32 v252, 2, v206
	v_xor_b32_e32 v252, v252, v187
	v_lshl_add_u32 v177, v252, 4, v215
	v_or_b32_e32 v252, 4, v206
	v_xor_b32_e32 v252, v252, v187
	v_lshl_add_u32 v178, v252, 4, v215
	v_or_b32_e32 v252, 6, v206
	v_xor_b32_e32 v252, v252, v187
	v_lshl_add_u32 v179, v252, 4, v215
	v_lshrrev_b32_e32 v253, 3, v208
	v_and_b32_e32 v210, 7, v208
	v_xor_b32_e32 v252, v210, v253
	v_lshl_add_u32 v180, v253, 7, v186
	v_lshl_add_u32 v180, v252, 4, v180
	v_lshl_add_u32 v252, v190, 7, v253
	v_add_u32_e32 v252, s30, v252
	v_lshlrev_b32_e32 v182, 10, v252
	v_bfe_u32 v252, v189, 6, 2
	v_lshl_add_u32 v182, v252, 7, v182
	v_lshl_add_u32 v182, v210, 4, v182
	v_mov_b32_e32 v183, 0
	s_and_b32 s36, s74, 1
	s_lshl_b32 s36, s36, 9
	s_and_b32 s37, s74, 4
	s_lshl_b32 s37, s37, 23
	s_add_u32 s36, s36, s37
	s_add_u32 s36, s78, s36
	s_addc_u32 s37, s79, 0
	v_lshl_add_u64 v[182:183], v[182:183], 0, s[36:37]
	s_mov_b32 s38, 0x2000
	s_mov_b32 s39, 0
	v_lshl_add_u64 v[240:241], v[182:183], 0, s[38:39]
	s_lshl_b32 s38, s38, 1
	v_cvt_pk_bf16_f32 v124, v124, v125
	v_cvt_pk_bf16_f32 v125, v126, v127
	ds_write_b64 v176, v[124:125] offset:0
	v_cvt_pk_bf16_f32 v120, v120, v121
	v_cvt_pk_bf16_f32 v121, v122, v123
	ds_write_b64 v177, v[120:121] offset:0
	v_cvt_pk_bf16_f32 v116, v116, v117
	v_cvt_pk_bf16_f32 v117, v118, v119
	ds_write_b64 v178, v[116:117] offset:0
	v_cvt_pk_bf16_f32 v112, v112, v113
	v_cvt_pk_bf16_f32 v113, v114, v115
	ds_write_b64 v179, v[112:113] offset:0
	v_cvt_pk_bf16_f32 v108, v108, v109
	v_cvt_pk_bf16_f32 v109, v110, v111
	ds_write_b64 v176, v[108:109] offset:2048
	v_cvt_pk_bf16_f32 v104, v104, v105
	v_cvt_pk_bf16_f32 v105, v106, v107
	ds_write_b64 v177, v[104:105] offset:2048
	v_cvt_pk_bf16_f32 v100, v100, v101
	v_cvt_pk_bf16_f32 v101, v102, v103
	ds_write_b64 v178, v[100:101] offset:2048
	v_cvt_pk_bf16_f32 v96, v96, v97
	v_cvt_pk_bf16_f32 v97, v98, v99
	ds_write_b64 v179, v[96:97] offset:2048
	v_cvt_pk_bf16_f32 v92, v92, v93
	v_cvt_pk_bf16_f32 v93, v94, v95
	ds_write_b64 v176, v[92:93] offset:4096
	v_cvt_pk_bf16_f32 v88, v88, v89
	v_cvt_pk_bf16_f32 v89, v90, v91
	ds_write_b64 v177, v[88:89] offset:4096
	v_cvt_pk_bf16_f32 v84, v84, v85
	v_cvt_pk_bf16_f32 v85, v86, v87
	ds_write_b64 v178, v[84:85] offset:4096
	v_cvt_pk_bf16_f32 v80, v80, v81
	v_cvt_pk_bf16_f32 v81, v82, v83
	ds_write_b64 v179, v[80:81] offset:4096
	v_cvt_pk_bf16_f32 v76, v76, v77
	v_cvt_pk_bf16_f32 v77, v78, v79
	ds_write_b64 v176, v[76:77] offset:6144
	v_cvt_pk_bf16_f32 v72, v72, v73
	v_cvt_pk_bf16_f32 v73, v74, v75
	ds_write_b64 v177, v[72:73] offset:6144
	v_cvt_pk_bf16_f32 v68, v68, v69
	v_cvt_pk_bf16_f32 v69, v70, v71
	ds_write_b64 v178, v[68:69] offset:6144
	v_cvt_pk_bf16_f32 v64, v64, v65
	v_cvt_pk_bf16_f32 v65, v66, v67
	ds_write_b64 v179, v[64:65] offset:6144
	v_cvt_pk_bf16_f32 v60, v60, v61
	v_cvt_pk_bf16_f32 v61, v62, v63
	ds_write_b64 v176, v[60:61] offset:8192
	v_cvt_pk_bf16_f32 v56, v56, v57
	v_cvt_pk_bf16_f32 v57, v58, v59
	ds_write_b64 v177, v[56:57] offset:8192
	v_cvt_pk_bf16_f32 v52, v52, v53
	v_cvt_pk_bf16_f32 v53, v54, v55
	ds_write_b64 v178, v[52:53] offset:8192
	v_cvt_pk_bf16_f32 v48, v48, v49
	v_cvt_pk_bf16_f32 v49, v50, v51
	ds_write_b64 v179, v[48:49] offset:8192
	v_cvt_pk_bf16_f32 v44, v44, v45
	v_cvt_pk_bf16_f32 v45, v46, v47
	ds_write_b64 v176, v[44:45] offset:10240
	v_cvt_pk_bf16_f32 v40, v40, v41
	v_cvt_pk_bf16_f32 v41, v42, v43
	ds_write_b64 v177, v[40:41] offset:10240
	v_cvt_pk_bf16_f32 v36, v36, v37
	v_cvt_pk_bf16_f32 v37, v38, v39
	ds_write_b64 v178, v[36:37] offset:10240
	v_cvt_pk_bf16_f32 v32, v32, v33
	v_cvt_pk_bf16_f32 v33, v34, v35
	ds_write_b64 v179, v[32:33] offset:10240
	v_cvt_pk_bf16_f32 v28, v28, v29
	v_cvt_pk_bf16_f32 v29, v30, v31
	ds_write_b64 v176, v[28:29] offset:12288
	v_cvt_pk_bf16_f32 v24, v24, v25
	v_cvt_pk_bf16_f32 v25, v26, v27
	ds_write_b64 v177, v[24:25] offset:12288
	v_cvt_pk_bf16_f32 v20, v20, v21
	v_cvt_pk_bf16_f32 v21, v22, v23
	ds_write_b64 v178, v[20:21] offset:12288
	v_cvt_pk_bf16_f32 v16, v16, v17
	v_cvt_pk_bf16_f32 v17, v18, v19
	ds_write_b64 v179, v[16:17] offset:12288
	v_cvt_pk_bf16_f32 v12, v12, v13
	v_cvt_pk_bf16_f32 v13, v14, v15
	ds_write_b64 v176, v[12:13] offset:14336
	v_cvt_pk_bf16_f32 v8, v8, v9
	v_cvt_pk_bf16_f32 v9, v10, v11
	ds_write_b64 v177, v[8:9] offset:14336
	v_cvt_pk_bf16_f32 v4, v4, v5
	v_cvt_pk_bf16_f32 v5, v6, v7
	ds_write_b64 v178, v[4:5] offset:14336
	v_cvt_pk_bf16_f32 v0, v0, v1
	v_cvt_pk_bf16_f32 v1, v2, v3
	ds_write_b64 v179, v[0:1] offset:14336
	s_waitcnt lgkmcnt(0)
; DI unsigned pack2bf(float a, float b) { const f2_t v = {a, b}; return __builtin_bit_cast(unsigned, __builtin_convertvector(v, bf2_t)); }
; DI void phase1(const Params& P, char* smem) {
;     ...
;       const int r = brow + row, c = bcol + col0;
;       const uint2 pk = make_uint2(pack2bf(v[0], v[1]), pack2bf(v[2], v[3]));
;       if (bcol < 512) {
;         const int g = c >> 4, hp = c & 15, m = r >> 6, j = r & 63;
;         *reinterpret_cast<uint2*>(UG + ((long)g * 512 + m) * UGLD + j * 16 + hp) = pk;
;       } else if (bcol < 1024) {
;         *reinterpret_cast<uint2*>(Qb + (long)r * 512 + (c - 512)) = pk;
;       } else if (bcol < 1536) {
;         *reinterpret_cast<uint2*>(Kb + (long)r * 512 + (c - 1024)) = pk;
	ds_read_b128 v[216:219], v180 offset:0
	ds_read_b128 v[220:223], v180 offset:1024
	ds_read_b128 v[224:227], v180 offset:2048
	ds_read_b128 v[228:231], v180 offset:3072
	s_waitcnt lgkmcnt(3)
	global_store_dwordx4 v[182:183], v[216:219], off
	s_nop 0
	v_lshl_add_u64 v[182:183], v[182:183], 0, s[38:39]
	s_waitcnt lgkmcnt(2)
	global_store_dwordx4 v[240:241], v[220:223], off
	s_nop 0
	v_lshl_add_u64 v[240:241], v[240:241], 0, s[38:39]
	s_waitcnt lgkmcnt(1)
	global_store_dwordx4 v[182:183], v[224:227], off
	s_nop 0
	v_lshl_add_u64 v[182:183], v[182:183], 0, s[38:39]
	s_waitcnt lgkmcnt(0)
	global_store_dwordx4 v[240:241], v[228:231], off
	s_nop 0
	v_lshl_add_u64 v[240:241], v[240:241], 0, s[38:39]
	ds_read_b128 v[232:235], v180 offset:4096
	ds_read_b128 v[236:239], v180 offset:5120
	ds_read_b128 v[244:247], v180 offset:6144
	ds_read_b128 v[248:251], v180 offset:7168
	s_waitcnt lgkmcnt(3)
	global_store_dwordx4 v[182:183], v[232:235], off
	s_nop 0
	v_lshl_add_u64 v[182:183], v[182:183], 0, s[38:39]
	s_waitcnt lgkmcnt(2)
	global_store_dwordx4 v[240:241], v[236:239], off
	s_nop 0
	v_lshl_add_u64 v[240:241], v[240:241], 0, s[38:39]
	s_waitcnt lgkmcnt(1)
	global_store_dwordx4 v[182:183], v[244:247], off
	s_nop 0
	v_lshl_add_u64 v[182:183], v[182:183], 0, s[38:39]
	s_waitcnt lgkmcnt(0)
	global_store_dwordx4 v[240:241], v[248:251], off
	s_nop 0
	v_lshl_add_u64 v[240:241], v[240:241], 0, s[38:39]
	ds_read_b128 v[216:219], v180 offset:8192
	ds_read_b128 v[220:223], v180 offset:9216
	ds_read_b128 v[224:227], v180 offset:10240
	ds_read_b128 v[228:231], v180 offset:11264
	s_waitcnt lgkmcnt(3)
	global_store_dwordx4 v[182:183], v[216:219], off
	s_nop 0
	v_lshl_add_u64 v[182:183], v[182:183], 0, s[38:39]
	s_waitcnt lgkmcnt(2)
	global_store_dwordx4 v[240:241], v[220:223], off
	s_nop 0
	v_lshl_add_u64 v[240:241], v[240:241], 0, s[38:39]
	s_waitcnt lgkmcnt(1)
	global_store_dwordx4 v[182:183], v[224:227], off
	s_nop 0
	v_lshl_add_u64 v[182:183], v[182:183], 0, s[38:39]
	s_waitcnt lgkmcnt(0)
	global_store_dwordx4 v[240:241], v[228:231], off
	s_nop 0
	v_lshl_add_u64 v[240:241], v[240:241], 0, s[38:39]
	ds_read_b128 v[232:235], v180 offset:12288
	ds_read_b128 v[236:239], v180 offset:13312
	ds_read_b128 v[244:247], v180 offset:14336
	ds_read_b128 v[248:251], v180 offset:15360
	s_waitcnt lgkmcnt(3)
	global_store_dwordx4 v[182:183], v[232:235], off
	s_nop 0
	v_lshl_add_u64 v[182:183], v[182:183], 0, s[38:39]
	s_waitcnt lgkmcnt(2)
	global_store_dwordx4 v[240:241], v[236:239], off
	s_nop 0
	v_lshl_add_u64 v[240:241], v[240:241], 0, s[38:39]
	s_waitcnt lgkmcnt(1)
	global_store_dwordx4 v[182:183], v[244:247], off
	s_nop 0
	v_lshl_add_u64 v[182:183], v[182:183], 0, s[38:39]
	s_waitcnt lgkmcnt(0)
	global_store_dwordx4 v[240:241], v[248:251], off
	s_nop 0
	v_lshl_add_u64 v[240:241], v[240:241], 0, s[38:39]
	v_or_b32_e32 v212, 0x50, v153
	v_or_b32_e32 v213, 0x60, v153
	s_branch .LBB0_106
.Lgemm_p1_u:
	v_or_b32_e32 v212, 0x50, v153
	v_or_b32_e32 v213, 0x60, v153
	s_mov_b64 s[4:5], -1
	s_and_b64 vcc, exec, s[10:11]
	s_waitcnt vmcnt(0) lgkmcnt(0)
	s_barrier
	v_add_u32_e32 v184, s30, v153
	v_cvt_pk_bf16_f32 v186, v124, v125
	v_cvt_pk_bf16_f32 v187, v126, v127
	s_cbranch_vccz .LBB0_119
	s_and_b64 vcc, exec, s[18:19]
	s_cbranch_vccz .LBB0_116
	s_and_b64 vcc, exec, s[24:25]
	s_cbranch_vccz .LBB0_113
	v_ashrrev_i32_e32 v215, 4, v184
	v_and_b32_e32 v215, 0xfffffe00, v215
	v_and_b32_e32 v185, 0x1f8f, v184
	v_add_u32_e32 v216, v215, v155
	v_lshlrev_b32_e32 v218, 1, v185
	v_mov_b32_e32 v219, v135
	v_ashrrev_i32_e32 v217, 31, v216
	v_lshl_add_u64 v[218:219], s[62:63], 0, v[218:219]
	v_lshlrev_b64 v[220:221], 14, v[216:217]
	v_cvt_pk_bf16_f32 v124, v124, s0
	v_lshl_add_u64 v[220:221], v[218:219], 0, v[220:221]
	global_store_short v[220:221], v124, off
	v_or_b32_e32 v124, 1, v216
	v_cvt_pk_bf16_f32 v185, v125, s0
	v_ashrrev_i32_e32 v125, 31, v124
	v_lshlrev_b64 v[124:125], 14, v[124:125]
	v_lshl_add_u64 v[124:125], v[218:219], 0, v[124:125]
	global_store_short v[124:125], v185, off
	v_or_b32_e32 v124, 2, v216
	v_ashrrev_i32_e32 v125, 31, v124
	v_lshlrev_b64 v[124:125], 14, v[124:125]
	v_cvt_pk_bf16_f32 v126, v126, s0
	v_lshl_add_u64 v[124:125], v[218:219], 0, v[124:125]
	global_store_short v[124:125], v126, off
	v_or_b32_e32 v124, 3, v216
	v_ashrrev_i32_e32 v125, 31, v124
	v_lshlrev_b64 v[124:125], 14, v[124:125]
	v_cvt_pk_bf16_f32 v126, v127, s0
	v_lshl_add_u64 v[124:125], v[218:219], 0, v[124:125]
	global_store_short v[124:125], v126, off
	s_mov_b64 s[4:5], 0

; template <class Epi>
; DI void gemm_tile256(const u16* __restrict__ Ag, long lda, const u16* __restrict__ Bg, long ldb, int nk, char* shm, Epi&& epi) {
;     ...
;   __syncthreads();
; #pragma unroll
;   for (int m = 0; m < 8; ++m)
; #pragma unroll
;     for (int n = 0; n < 4; ++n) epi(wr * 128 + m * 16 + fr, wc * 64 + n * 16 + fq * 4, acc[m][n]);
; DI void phase6(const Params& P, char* smem) {
;     ...
;     gemm_tile256(cat + (long)brow * 1024, 1024, WoT + (long)bcol * 1024, 1024, 32, smem, [&](int row, int col0, f32x4 v) {
;       const long o = (long)(brow + row) * 1024 + bcol + col0;
;       const float4 xs = *reinterpret_cast<const float4*>(P.x + o);
;       *reinterpret_cast<float4*>(Z1 + o) = make_float4(ALPHA * xs.x + v[0], ALPHA * xs.y + v[1], ALPHA * xs.z + v[2], ALPHA * xs.w + v[3]);
;     });
.Lgemm_p6_kend:
	s_nop 7
	s_nop 3
	s_waitcnt vmcnt(0) lgkmcnt(0)
	s_barrier
	v_and_b32_e32 v196, 15, v208
	v_lshrrev_b32_e32 v197, 4, v208
	v_lshrrev_b32_e32 v198, 6, v189
	v_lshlrev_b32_e32 v198, 14, v198
	v_lshl_add_u32 v201, v196, 8, v198
	v_or_b32_e32 v199, 0, v197
	v_xor_b32_e32 v199, v199, v196
	v_lshl_add_u32 v206, v199, 4, v201
	v_or_b32_e32 v199, 4, v197
	v_xor_b32_e32 v199, v199, v196
	v_lshl_add_u32 v207, v199, 4, v201
	v_or_b32_e32 v199, 8, v197
	v_xor_b32_e32 v199, v199, v196
	v_lshl_add_u32 v210, v199, 4, v201
	v_or_b32_e32 v199, 12, v197
	v_xor_b32_e32 v199, v199, v196
	v_lshl_add_u32 v211, v199, 4, v201
	v_add_u32_e32 v200, 0, v197
	v_xor_b32_e32 v199, v196, v200
	v_lshl_add_u32 v212, v200, 8, v198
	v_lshl_add_u32 v212, v199, 4, v212
	v_add_u32_e32 v200, 4, v197
	v_xor_b32_e32 v199, v196, v200
	v_lshl_add_u32 v213, v200, 8, v198
	v_lshl_add_u32 v213, v199, 4, v213
	v_add_u32_e32 v200, 8, v197
	v_xor_b32_e32 v199, v196, v200
	v_lshl_add_u32 v214, v200, 8, v198
	v_lshl_add_u32 v214, v199, 4, v214
	v_add_u32_e32 v200, 12, v197
	v_xor_b32_e32 v199, v196, v200
	v_lshl_add_u32 v215, v200, 8, v198
	v_lshl_add_u32 v215, v199, 4, v215
	v_lshl_add_u32 v199, v190, 7, v197
	v_add_u32_e32 v199, s10, v199
	v_lshlrev_b32_e32 v216, 12, v199
	v_bfe_u32 v199, v189, 6, 2
	v_lshl_add_u32 v216, v199, 8, v216
	v_lshl_add_u32 v216, v196, 4, v216
	s_and_b32 s26, s74, 3
	s_lshl_b32 s26, s26, 10
	v_add_u32_e32 v216, s26, v216
	v_add_u32_e32 v201, 0x0, v216
	global_load_dwordx4 v[218:221], v201, s[52:53]
	v_add_u32_e32 v202, 0x4000, v216
	global_load_dwordx4 v[222:225], v202, s[52:53]
	v_add_u32_e32 v201, 0x8000, v216
	global_load_dwordx4 v[226:229], v201, s[52:53]
	v_add_u32_e32 v202, 0xc000, v216
	global_load_dwordx4 v[230:233], v202, s[52:53]
	v_add_u32_e32 v201, 0x10000, v216
	global_load_dwordx4 v[234:237], v201, s[52:53]
	v_add_u32_e32 v202, 0x14000, v216
	global_load_dwordx4 v[238:241], v202, s[52:53]
	v_add_u32_e32 v201, 0x18000, v216
	global_load_dwordx4 v[242:245], v201, s[52:53]
	v_add_u32_e32 v202, 0x1c000, v216
	global_load_dwordx4 v[246:249], v202, s[52:53]
	ds_write_b128 v206, v[124:127] offset:0
	ds_write_b128 v207, v[120:123] offset:0
	ds_write_b128 v210, v[116:119] offset:0
	ds_write_b128 v211, v[112:115] offset:0
	ds_write_b128 v206, v[108:111] offset:4096
	ds_write_b128 v207, v[104:107] offset:4096
	ds_write_b128 v210, v[100:103] offset:4096
	ds_write_b128 v211, v[96:99] offset:4096
	ds_write_b128 v206, v[92:95] offset:8192
	ds_write_b128 v207, v[88:91] offset:8192
	ds_write_b128 v210, v[84:87] offset:8192
	ds_write_b128 v211, v[80:83] offset:8192
	ds_write_b128 v206, v[76:79] offset:12288
	ds_write_b128 v207, v[72:75] offset:12288
	ds_write_b128 v210, v[68:71] offset:12288
	ds_write_b128 v211, v[64:67] offset:12288
	s_waitcnt lgkmcnt(0)
	v_add_u32_e32 v201, 0x20000, v216
	global_load_dwordx4 v[64:67], v201, s[52:53]
	v_add_u32_e32 v202, 0x24000, v216
	global_load_dwordx4 v[68:71], v202, s[52:53]
	v_add_u32_e32 v201, 0x28000, v216
	global_load_dwordx4 v[72:75], v201, s[52:53]
	v_add_u32_e32 v202, 0x2c000, v216
	global_load_dwordx4 v[76:79], v202, s[52:53]
	v_add_u32_e32 v201, 0x30000, v216
	global_load_dwordx4 v[80:83], v201, s[52:53]
	v_add_u32_e32 v202, 0x34000, v216
	global_load_dwordx4 v[84:87], v202, s[52:53]
	v_add_u32_e32 v201, 0x38000, v216
	global_load_dwordx4 v[88:91], v201, s[52:53]
	v_add_u32_e32 v202, 0x3c000, v216
	global_load_dwordx4 v[92:95], v202, s[52:53]
	ds_read_b128 v[96:99], v212 offset:0
	ds_read_b128 v[100:103], v213 offset:0
	ds_read_b128 v[104:107], v214 offset:0
	ds_read_b128 v[108:111], v215 offset:0
	ds_read_b128 v[112:115], v212 offset:4096
	ds_read_b128 v[116:119], v213 offset:4096
	ds_read_b128 v[120:123], v214 offset:4096
	ds_read_b128 v[124:127], v215 offset:4096
	s_waitcnt vmcnt(8)
	s_waitcnt lgkmcnt(7)
	v_pk_fma_f32 v[218:219], v[218:219], s[6:7], v[96:97] op_sel_hi:[1,0,1]
	v_pk_fma_f32 v[220:221], v[220:221], s[6:7], v[98:99] op_sel_hi:[1,0,1]
	v_add_u32_e32 v201, 0x0, v216
	global_store_dwordx4 v201, v[218:221], s[38:39]
	s_waitcnt lgkmcnt(6)
	v_pk_fma_f32 v[222:223], v[222:223], s[6:7], v[100:101] op_sel_hi:[1,0,1]
	v_pk_fma_f32 v[224:225], v[224:225], s[6:7], v[102:103] op_sel_hi:[1,0,1]
	v_add_u32_e32 v202, 0x4000, v216
	global_store_dwordx4 v202, v[222:225], s[38:39]
	s_waitcnt lgkmcnt(5)
	v_pk_fma_f32 v[226:227], v[226:227], s[6:7], v[104:105] op_sel_hi:[1,0,1]
	v_pk_fma_f32 v[228:229], v[228:229], s[6:7], v[106:107] op_sel_hi:[1,0,1]
	v_add_u32_e32 v201, 0x8000, v216
	global_store_dwordx4 v201, v[226:229], s[38:39]
	s_waitcnt lgkmcnt(4)
	v_pk_fma_f32 v[230:231], v[230:231], s[6:7], v[108:109] op_sel_hi:[1,0,1]
	v_pk_fma_f32 v[232:233], v[232:233], s[6:7], v[110:111] op_sel_hi:[1,0,1]
	v_add_u32_e32 v202, 0xc000, v216
	global_store_dwordx4 v202, v[230:233], s[38:39]
	s_waitcnt lgkmcnt(3)
	v_pk_fma_f32 v[234:235], v[234:235], s[6:7], v[112:113] op_sel_hi:[1,0,1]
	v_pk_fma_f32 v[236:237], v[236:237], s[6:7], v[114:115] op_sel_hi:[1,0,1]
	v_add_u32_e32 v201, 0x10000, v216
	global_store_dwordx4 v201, v[234:237], s[38:39]
	s_waitcnt lgkmcnt(2)
	v_pk_fma_f32 v[238:239], v[238:239], s[6:7], v[116:117] op_sel_hi:[1,0,1]
	v_pk_fma_f32 v[240:241], v[240:241], s[6:7], v[118:119] op_sel_hi:[1,0,1]
	v_add_u32_e32 v202, 0x14000, v216
	global_store_dwordx4 v202, v[238:241], s[38:39]
	s_waitcnt lgkmcnt(1)
	v_pk_fma_f32 v[242:243], v[242:243], s[6:7], v[120:121] op_sel_hi:[1,0,1]
	v_pk_fma_f32 v[244:245], v[244:245], s[6:7], v[122:123] op_sel_hi:[1,0,1]
	v_add_u32_e32 v201, 0x18000, v216
	global_store_dwordx4 v201, v[242:245], s[38:39]
	s_waitcnt lgkmcnt(0)
; DI void phase6(const Params& P, char* smem) {
;     ...
;     gemm_tile256(cat + (long)brow * 1024, 1024, WoT + (long)bcol * 1024, 1024, 32, smem, [&](int row, int col0, f32x4 v) {
;       const long o = (long)(brow + row) * 1024 + bcol + col0;
;       const float4 xs = *reinterpret_cast<const float4*>(P.x + o);
;       *reinterpret_cast<float4*>(Z1 + o) = make_float4(ALPHA * xs.x + v[0], ALPHA * xs.y + v[1], ALPHA * xs.z + v[2], ALPHA * xs.w + v[3]);
;     });
	v_pk_fma_f32 v[246:247], v[246:247], s[6:7], v[124:125] op_sel_hi:[1,0,1]
	v_pk_fma_f32 v[248:249], v[248:249], s[6:7], v[126:127] op_sel_hi:[1,0,1]
	v_add_u32_e32 v202, 0x1c000, v216
	global_store_dwordx4 v202, v[246:249], s[38:39]
	ds_read_b128 v[96:99], v212 offset:8192
	ds_read_b128 v[100:103], v213 offset:8192
	ds_read_b128 v[104:107], v214 offset:8192
	ds_read_b128 v[108:111], v215 offset:8192
	ds_read_b128 v[112:115], v212 offset:12288
	ds_read_b128 v[116:119], v213 offset:12288
	ds_read_b128 v[120:123], v214 offset:12288
	ds_read_b128 v[124:127], v215 offset:12288
	s_waitcnt vmcnt(0)
	s_waitcnt lgkmcnt(7)
	v_pk_fma_f32 v[64:65], v[64:65], s[6:7], v[96:97] op_sel_hi:[1,0,1]
	v_pk_fma_f32 v[66:67], v[66:67], s[6:7], v[98:99] op_sel_hi:[1,0,1]
	v_add_u32_e32 v201, 0x20000, v216
	global_store_dwordx4 v201, v[64:67], s[38:39]
	s_waitcnt lgkmcnt(6)
	v_pk_fma_f32 v[68:69], v[68:69], s[6:7], v[100:101] op_sel_hi:[1,0,1]
	v_pk_fma_f32 v[70:71], v[70:71], s[6:7], v[102:103] op_sel_hi:[1,0,1]
	v_add_u32_e32 v202, 0x24000, v216
	global_store_dwordx4 v202, v[68:71], s[38:39]
	s_waitcnt lgkmcnt(5)
	v_pk_fma_f32 v[72:73], v[72:73], s[6:7], v[104:105] op_sel_hi:[1,0,1]
	v_pk_fma_f32 v[74:75], v[74:75], s[6:7], v[106:107] op_sel_hi:[1,0,1]
	v_add_u32_e32 v201, 0x28000, v216
	global_store_dwordx4 v201, v[72:75], s[38:39]
	s_waitcnt lgkmcnt(4)
	v_pk_fma_f32 v[76:77], v[76:77], s[6:7], v[108:109] op_sel_hi:[1,0,1]
	v_pk_fma_f32 v[78:79], v[78:79], s[6:7], v[110:111] op_sel_hi:[1,0,1]
	v_add_u32_e32 v202, 0x2c000, v216
	global_store_dwordx4 v202, v[76:79], s[38:39]
	s_waitcnt lgkmcnt(3)
	v_pk_fma_f32 v[80:81], v[80:81], s[6:7], v[112:113] op_sel_hi:[1,0,1]
	v_pk_fma_f32 v[82:83], v[82:83], s[6:7], v[114:115] op_sel_hi:[1,0,1]
	v_add_u32_e32 v201, 0x30000, v216
	global_store_dwordx4 v201, v[80:83], s[38:39]
	s_waitcnt lgkmcnt(2)
	v_pk_fma_f32 v[84:85], v[84:85], s[6:7], v[116:117] op_sel_hi:[1,0,1]
	v_pk_fma_f32 v[86:87], v[86:87], s[6:7], v[118:119] op_sel_hi:[1,0,1]
	v_add_u32_e32 v202, 0x34000, v216
	global_store_dwordx4 v202, v[84:87], s[38:39]
	s_waitcnt lgkmcnt(1)
	v_pk_fma_f32 v[88:89], v[88:89], s[6:7], v[120:121] op_sel_hi:[1,0,1]
	v_pk_fma_f32 v[90:91], v[90:91], s[6:7], v[122:123] op_sel_hi:[1,0,1]
	v_add_u32_e32 v201, 0x38000, v216
	global_store_dwordx4 v201, v[88:91], s[38:39]
	s_waitcnt lgkmcnt(0)
	v_pk_fma_f32 v[92:93], v[92:93], s[6:7], v[124:125] op_sel_hi:[1,0,1]
	v_pk_fma_f32 v[94:95], v[94:95], s[6:7], v[126:127] op_sel_hi:[1,0,1]
	v_add_u32_e32 v202, 0x3c000, v216
	global_store_dwordx4 v202, v[92:95], s[38:39]
	s_waitcnt lgkmcnt(0)
	v_add_u32_e32 v201, 0x40000, v216
	global_load_dwordx4 v[218:221], v201, s[52:53]
	v_add_u32_e32 v202, 0x44000, v216
	global_load_dwordx4 v[222:225], v202, s[52:53]
	v_add_u32_e32 v201, 0x48000, v216
	global_load_dwordx4 v[226:229], v201, s[52:53]
	v_add_u32_e32 v202, 0x4c000, v216
	global_load_dwordx4 v[230:233], v202, s[52:53]
	v_add_u32_e32 v201, 0x50000, v216
	global_load_dwordx4 v[234:237], v201, s[52:53]
	v_add_u32_e32 v202, 0x54000, v216
	global_load_dwordx4 v[238:241], v202, s[52:53]
	v_add_u32_e32 v201, 0x58000, v216
	global_load_dwordx4 v[242:245], v201, s[52:53]
	v_add_u32_e32 v202, 0x5c000, v216
	global_load_dwordx4 v[246:249], v202, s[52:53]
	ds_write_b128 v206, v[60:63] offset:0
	ds_write_b128 v207, v[56:59] offset:0
	ds_write_b128 v210, v[52:55] offset:0
	ds_write_b128 v211, v[48:51] offset:0
	ds_write_b128 v206, v[44:47] offset:4096
	ds_write_b128 v207, v[40:43] offset:4096
	ds_write_b128 v210, v[36:39] offset:4096
	ds_write_b128 v211, v[32:35] offset:4096
	ds_write_b128 v206, v[28:31] offset:8192
	ds_write_b128 v207, v[24:27] offset:8192
	ds_write_b128 v210, v[20:23] offset:8192
	ds_write_b128 v211, v[16:19] offset:8192
	ds_write_b128 v206, v[12:15] offset:12288
	ds_write_b128 v207, v[8:11] offset:12288
	ds_write_b128 v210, v[4:7] offset:12288
	ds_write_b128 v211, v[0:3] offset:12288
	s_waitcnt lgkmcnt(0)
	v_add_u32_e32 v201, 0x60000, v216
	global_load_dwordx4 v[64:67], v201, s[52:53]
	v_add_u32_e32 v202, 0x64000, v216
	global_load_dwordx4 v[68:71], v202, s[52:53]
	v_add_u32_e32 v201, 0x68000, v216
	global_load_dwordx4 v[72:75], v201, s[52:53]
	v_add_u32_e32 v202, 0x6c000, v216
	global_load_dwordx4 v[76:79], v202, s[52:53]
	v_add_u32_e32 v201, 0x70000, v216
	global_load_dwordx4 v[80:83], v201, s[52:53]
	v_add_u32_e32 v202, 0x74000, v216
	global_load_dwordx4 v[84:87], v202, s[52:53]
	v_add_u32_e32 v201, 0x78000, v216
	global_load_dwordx4 v[88:91], v201, s[52:53]
	v_add_u32_e32 v202, 0x7c000, v216
	global_load_dwordx4 v[92:95], v202, s[52:53]
	ds_read_b128 v[96:99], v212 offset:0
	ds_read_b128 v[100:103], v213 offset:0
	ds_read_b128 v[104:107], v214 offset:0
	ds_read_b128 v[108:111], v215 offset:0
	ds_read_b128 v[112:115], v212 offset:4096
	ds_read_b128 v[116:119], v213 offset:4096
	ds_read_b128 v[120:123], v214 offset:4096
	ds_read_b128 v[124:127], v215 offset:4096
	s_waitcnt vmcnt(8)
; DI void phase6(const Params& P, char* smem) {
;     ...
;   for (int q = RBLK >> 3; q < 64; q += RGRID >> 3) {
;     const int brow = (q * 2 + ((RBLK & 7) >> 2)) * 256, bcol = (RBLK & 3) * 256;
;     gemm_tile256(cat + (long)brow * 1024, 1024, WoT + (long)bcol * 1024, 1024, 32, smem, [&](int row, int col0, f32x4 v) {
;       const long o = (long)(brow + row) * 1024 + bcol + col0;
;       const float4 xs = *reinterpret_cast<const float4*>(P.x + o);
;       *reinterpret_cast<float4*>(Z1 + o) = make_float4(ALPHA * xs.x + v[0], ALPHA * xs.y + v[1], ALPHA * xs.z + v[2], ALPHA * xs.w + v[3]);
;     });
	s_waitcnt lgkmcnt(7)
	v_pk_fma_f32 v[218:219], v[218:219], s[6:7], v[96:97] op_sel_hi:[1,0,1]
	v_pk_fma_f32 v[220:221], v[220:221], s[6:7], v[98:99] op_sel_hi:[1,0,1]
	v_add_u32_e32 v201, 0x40000, v216
	global_store_dwordx4 v201, v[218:221], s[38:39]
	s_waitcnt lgkmcnt(6)
	v_pk_fma_f32 v[222:223], v[222:223], s[6:7], v[100:101] op_sel_hi:[1,0,1]
	v_pk_fma_f32 v[224:225], v[224:225], s[6:7], v[102:103] op_sel_hi:[1,0,1]
	v_add_u32_e32 v202, 0x44000, v216
	global_store_dwordx4 v202, v[222:225], s[38:39]
	s_waitcnt lgkmcnt(5)
	v_pk_fma_f32 v[226:227], v[226:227], s[6:7], v[104:105] op_sel_hi:[1,0,1]
	v_pk_fma_f32 v[228:229], v[228:229], s[6:7], v[106:107] op_sel_hi:[1,0,1]
	v_add_u32_e32 v201, 0x48000, v216
	global_store_dwordx4 v201, v[226:229], s[38:39]
	s_waitcnt lgkmcnt(4)
	v_pk_fma_f32 v[230:231], v[230:231], s[6:7], v[108:109] op_sel_hi:[1,0,1]
	v_pk_fma_f32 v[232:233], v[232:233], s[6:7], v[110:111] op_sel_hi:[1,0,1]
	v_add_u32_e32 v202, 0x4c000, v216
	global_store_dwordx4 v202, v[230:233], s[38:39]
	s_waitcnt lgkmcnt(3)
	v_pk_fma_f32 v[234:235], v[234:235], s[6:7], v[112:113] op_sel_hi:[1,0,1]
	v_pk_fma_f32 v[236:237], v[236:237], s[6:7], v[114:115] op_sel_hi:[1,0,1]
	v_add_u32_e32 v201, 0x50000, v216
	global_store_dwordx4 v201, v[234:237], s[38:39]
	s_waitcnt lgkmcnt(2)
	v_pk_fma_f32 v[238:239], v[238:239], s[6:7], v[116:117] op_sel_hi:[1,0,1]
	v_pk_fma_f32 v[240:241], v[240:241], s[6:7], v[118:119] op_sel_hi:[1,0,1]
	v_add_u32_e32 v202, 0x54000, v216
	global_store_dwordx4 v202, v[238:241], s[38:39]
	s_waitcnt lgkmcnt(1)
	v_pk_fma_f32 v[242:243], v[242:243], s[6:7], v[120:121] op_sel_hi:[1,0,1]
	v_pk_fma_f32 v[244:245], v[244:245], s[6:7], v[122:123] op_sel_hi:[1,0,1]
	v_add_u32_e32 v201, 0x58000, v216
	global_store_dwordx4 v201, v[242:245], s[38:39]
	s_waitcnt lgkmcnt(0)
	v_pk_fma_f32 v[246:247], v[246:247], s[6:7], v[124:125] op_sel_hi:[1,0,1]
	v_pk_fma_f32 v[248:249], v[248:249], s[6:7], v[126:127] op_sel_hi:[1,0,1]
	v_add_u32_e32 v202, 0x5c000, v216
	global_store_dwordx4 v202, v[246:249], s[38:39]
	ds_read_b128 v[96:99], v212 offset:8192
	ds_read_b128 v[100:103], v213 offset:8192
	ds_read_b128 v[104:107], v214 offset:8192
	ds_read_b128 v[108:111], v215 offset:8192
	ds_read_b128 v[112:115], v212 offset:12288
	ds_read_b128 v[116:119], v213 offset:12288
	ds_read_b128 v[120:123], v214 offset:12288
	ds_read_b128 v[124:127], v215 offset:12288
	s_waitcnt vmcnt(0)
	s_waitcnt lgkmcnt(7)
	v_pk_fma_f32 v[64:65], v[64:65], s[6:7], v[96:97] op_sel_hi:[1,0,1]
	v_pk_fma_f32 v[66:67], v[66:67], s[6:7], v[98:99] op_sel_hi:[1,0,1]
	v_add_u32_e32 v201, 0x60000, v216
	global_store_dwordx4 v201, v[64:67], s[38:39]
	s_waitcnt lgkmcnt(6)
	v_pk_fma_f32 v[68:69], v[68:69], s[6:7], v[100:101] op_sel_hi:[1,0,1]
	v_pk_fma_f32 v[70:71], v[70:71], s[6:7], v[102:103] op_sel_hi:[1,0,1]
	v_add_u32_e32 v202, 0x64000, v216
	global_store_dwordx4 v202, v[68:71], s[38:39]
	s_waitcnt lgkmcnt(5)
	v_pk_fma_f32 v[72:73], v[72:73], s[6:7], v[104:105] op_sel_hi:[1,0,1]
	v_pk_fma_f32 v[74:75], v[74:75], s[6:7], v[106:107] op_sel_hi:[1,0,1]
	v_add_u32_e32 v201, 0x68000, v216
	global_store_dwordx4 v201, v[72:75], s[38:39]
	s_waitcnt lgkmcnt(4)
	v_pk_fma_f32 v[76:77], v[76:77], s[6:7], v[108:109] op_sel_hi:[1,0,1]
	v_pk_fma_f32 v[78:79], v[78:79], s[6:7], v[110:111] op_sel_hi:[1,0,1]
	v_add_u32_e32 v202, 0x6c000, v216
	global_store_dwordx4 v202, v[76:79], s[38:39]
	s_waitcnt lgkmcnt(3)
	v_pk_fma_f32 v[80:81], v[80:81], s[6:7], v[112:113] op_sel_hi:[1,0,1]
	v_pk_fma_f32 v[82:83], v[82:83], s[6:7], v[114:115] op_sel_hi:[1,0,1]
	v_add_u32_e32 v201, 0x70000, v216
	global_store_dwordx4 v201, v[80:83], s[38:39]
	s_waitcnt lgkmcnt(2)
	v_pk_fma_f32 v[84:85], v[84:85], s[6:7], v[116:117] op_sel_hi:[1,0,1]
	v_pk_fma_f32 v[86:87], v[86:87], s[6:7], v[118:119] op_sel_hi:[1,0,1]
	v_add_u32_e32 v202, 0x74000, v216
	global_store_dwordx4 v202, v[84:87], s[38:39]
	s_waitcnt lgkmcnt(1)
	v_pk_fma_f32 v[88:89], v[88:89], s[6:7], v[120:121] op_sel_hi:[1,0,1]
	v_pk_fma_f32 v[90:91], v[90:91], s[6:7], v[122:123] op_sel_hi:[1,0,1]
	v_add_u32_e32 v201, 0x78000, v216
	global_store_dwordx4 v201, v[88:91], s[38:39]
	s_waitcnt lgkmcnt(0)
	v_pk_fma_f32 v[92:93], v[92:93], s[6:7], v[124:125] op_sel_hi:[1,0,1]
	v_pk_fma_f32 v[94:95], v[94:95], s[6:7], v[126:127] op_sel_hi:[1,0,1]
	v_add_u32_e32 v202, 0x7c000, v216
	global_store_dwordx4 v202, v[92:95], s[38:39]
	s_add_i32 s15, s15, s9
	s_add_i32 s4, s4, s14
	s_cmp_lt_i32 s15, 64
	s_cbranch_scc1 .LBB0_946

; DI unsigned pack2bf(float a, float b) { const f2_t v = {a, b}; return __builtin_bit_cast(unsigned, __builtin_convertvector(v, bf2_t)); }
; template <class Epi>
; DI void gemm_tile256(const u16* __restrict__ Ag, long lda, const u16* __restrict__ Bg, long ldb, int nk, char* shm, Epi&& epi) {
;     ...
;   __syncthreads();
; #pragma unroll
;   for (int m = 0; m < 8; ++m)
; #pragma unroll
;     for (int n = 0; n < 4; ++n) epi(wr * 128 + m * 16 + fr, wc * 64 + n * 16 + fq * 4, acc[m][n]);
; DI void phase8(const Params& P, char* smem) {
;     ...
;   for (int q = RBLK >> 3; q < 128; q += RGRID >> 3) {
;     const int brow = q * 256, bcol = (RBLK & 7) * 256;
;     gemm_tile256(h1b + (long)brow * 1024, 1024, WqT + (long)bcol * 1024, 1024, 32, smem, [&](int row, int col0, f32x4 v) {
;       *reinterpret_cast<uint2*>(Qp + (long)(brow + row) * 2048 + bcol + col0) = make_uint2(pack2bf(v[0], v[1]), pack2bf(v[2], v[3]));
;     });
.Lgemm_p8_kend:
	s_nop 7
	s_nop 3
	s_waitcnt vmcnt(0) lgkmcnt(0)
	s_barrier
	v_and_b32_e32 v186, 15, v208
	v_lshrrev_b32_e32 v187, 4, v208
	v_lshrrev_b32_e32 v206, 6, v189
	v_lshlrev_b32_e32 v206, 14, v206
	v_and_b32_e32 v207, 7, v186
	v_lshrrev_b32_e32 v224, 1, v187
	v_and_b32_e32 v225, 1, v187
	v_lshl_add_u32 v226, v186, 7, v206
	v_lshl_add_u32 v226, v225, 3, v226
	v_or_b32_e32 v227, 0, v224
	v_xor_b32_e32 v227, v227, v207
	v_lshl_add_u32 v232, v227, 4, v226
	v_or_b32_e32 v227, 2, v224
	v_xor_b32_e32 v227, v227, v207
	v_lshl_add_u32 v233, v227, 4, v226
	v_or_b32_e32 v227, 4, v224
	v_xor_b32_e32 v227, v227, v207
	v_lshl_add_u32 v234, v227, 4, v226
	v_or_b32_e32 v227, 6, v224
	v_xor_b32_e32 v227, v227, v207
	v_lshl_add_u32 v235, v227, 4, v226
	v_lshrrev_b32_e32 v228, 3, v208
	v_and_b32_e32 v229, 7, v208
	v_xor_b32_e32 v227, v229, v228
	v_lshl_add_u32 v236, v228, 7, v206
	v_lshl_add_u32 v236, v227, 4, v236
	v_lshl_add_u32 v227, v190, 7, v228
	v_add_u32_e32 v227, s10, v227
	v_lshlrev_b32_e32 v238, 12, v227
	v_bfe_u32 v227, v189, 6, 2
	v_lshl_add_u32 v238, v227, 7, v238
	v_lshl_add_u32 v238, v229, 4, v238
	v_mov_b32_e32 v239, 0
	s_and_b32 s26, s74, 7
	s_lshl_b32 s26, s26, 9
	s_add_u32 s26, s26, 0x8000000
	s_add_u32 s26, s78, s26
	s_addc_u32 s27, s79, 0
	v_lshl_add_u64 v[238:239], v[238:239], 0, s[26:27]
	s_mov_b32 s28, 0x8000
	s_mov_b32 s29, 0
	v_lshl_add_u64 v[240:241], v[238:239], 0, s[28:29]
	s_lshl_b32 s28, s28, 1
	v_cvt_pk_bf16_f32 v124, v124, v125
	v_cvt_pk_bf16_f32 v125, v126, v127
	ds_write_b64 v232, v[124:125] offset:0
	v_cvt_pk_bf16_f32 v120, v120, v121
	v_cvt_pk_bf16_f32 v121, v122, v123
	ds_write_b64 v233, v[120:121] offset:0
	v_cvt_pk_bf16_f32 v116, v116, v117
	v_cvt_pk_bf16_f32 v117, v118, v119
	ds_write_b64 v234, v[116:117] offset:0
	v_cvt_pk_bf16_f32 v112, v112, v113
	v_cvt_pk_bf16_f32 v113, v114, v115
	ds_write_b64 v235, v[112:113] offset:0
	v_cvt_pk_bf16_f32 v108, v108, v109
	v_cvt_pk_bf16_f32 v109, v110, v111
	ds_write_b64 v232, v[108:109] offset:2048
	v_cvt_pk_bf16_f32 v104, v104, v105
	v_cvt_pk_bf16_f32 v105, v106, v107
	ds_write_b64 v233, v[104:105] offset:2048
	v_cvt_pk_bf16_f32 v100, v100, v101
	v_cvt_pk_bf16_f32 v101, v102, v103
	ds_write_b64 v234, v[100:101] offset:2048
	v_cvt_pk_bf16_f32 v96, v96, v97
	v_cvt_pk_bf16_f32 v97, v98, v99
	ds_write_b64 v235, v[96:97] offset:2048
	v_cvt_pk_bf16_f32 v92, v92, v93
	v_cvt_pk_bf16_f32 v93, v94, v95
	ds_write_b64 v232, v[92:93] offset:4096
	v_cvt_pk_bf16_f32 v88, v88, v89
	v_cvt_pk_bf16_f32 v89, v90, v91
	ds_write_b64 v233, v[88:89] offset:4096
	v_cvt_pk_bf16_f32 v84, v84, v85
	v_cvt_pk_bf16_f32 v85, v86, v87
	ds_write_b64 v234, v[84:85] offset:4096
	v_cvt_pk_bf16_f32 v80, v80, v81
	v_cvt_pk_bf16_f32 v81, v82, v83
	ds_write_b64 v235, v[80:81] offset:4096
	v_cvt_pk_bf16_f32 v76, v76, v77
	v_cvt_pk_bf16_f32 v77, v78, v79
	ds_write_b64 v232, v[76:77] offset:6144
	v_cvt_pk_bf16_f32 v72, v72, v73
	v_cvt_pk_bf16_f32 v73, v74, v75
	ds_write_b64 v233, v[72:73] offset:6144
	v_cvt_pk_bf16_f32 v68, v68, v69
	v_cvt_pk_bf16_f32 v69, v70, v71
	ds_write_b64 v234, v[68:69] offset:6144
	v_cvt_pk_bf16_f32 v64, v64, v65
	v_cvt_pk_bf16_f32 v65, v66, v67
	ds_write_b64 v235, v[64:65] offset:6144
	v_cvt_pk_bf16_f32 v60, v60, v61
	v_cvt_pk_bf16_f32 v61, v62, v63
	ds_write_b64 v232, v[60:61] offset:8192
	v_cvt_pk_bf16_f32 v56, v56, v57
	v_cvt_pk_bf16_f32 v57, v58, v59
	ds_write_b64 v233, v[56:57] offset:8192
	v_cvt_pk_bf16_f32 v52, v52, v53
	v_cvt_pk_bf16_f32 v53, v54, v55
	ds_write_b64 v234, v[52:53] offset:8192
	v_cvt_pk_bf16_f32 v48, v48, v49
	v_cvt_pk_bf16_f32 v49, v50, v51
	ds_write_b64 v235, v[48:49] offset:8192
	v_cvt_pk_bf16_f32 v44, v44, v45
	v_cvt_pk_bf16_f32 v45, v46, v47
	ds_write_b64 v232, v[44:45] offset:10240
	v_cvt_pk_bf16_f32 v40, v40, v41
	v_cvt_pk_bf16_f32 v41, v42, v43
	ds_write_b64 v233, v[40:41] offset:10240
	v_cvt_pk_bf16_f32 v36, v36, v37
	v_cvt_pk_bf16_f32 v37, v38, v39
	ds_write_b64 v234, v[36:37] offset:10240
	v_cvt_pk_bf16_f32 v32, v32, v33
	v_cvt_pk_bf16_f32 v33, v34, v35
	ds_write_b64 v235, v[32:33] offset:10240
	v_cvt_pk_bf16_f32 v28, v28, v29
	v_cvt_pk_bf16_f32 v29, v30, v31
	ds_write_b64 v232, v[28:29] offset:12288
	v_cvt_pk_bf16_f32 v24, v24, v25
	v_cvt_pk_bf16_f32 v25, v26, v27
	ds_write_b64 v233, v[24:25] offset:12288
	v_cvt_pk_bf16_f32 v20, v20, v21
	v_cvt_pk_bf16_f32 v21, v22, v23
	ds_write_b64 v234, v[20:21] offset:12288
	v_cvt_pk_bf16_f32 v16, v16, v17
	v_cvt_pk_bf16_f32 v17, v18, v19
	ds_write_b64 v235, v[16:17] offset:12288
	v_cvt_pk_bf16_f32 v12, v12, v13
	v_cvt_pk_bf16_f32 v13, v14, v15
	ds_write_b64 v232, v[12:13] offset:14336
	v_cvt_pk_bf16_f32 v8, v8, v9
	v_cvt_pk_bf16_f32 v9, v10, v11
	ds_write_b64 v233, v[8:9] offset:14336
	v_cvt_pk_bf16_f32 v4, v4, v5
	v_cvt_pk_bf16_f32 v5, v6, v7
	ds_write_b64 v234, v[4:5] offset:14336
	v_cvt_pk_bf16_f32 v0, v0, v1
	v_cvt_pk_bf16_f32 v1, v2, v3
	ds_write_b64 v235, v[0:1] offset:14336
	s_waitcnt lgkmcnt(0)
; DI unsigned pack2bf(float a, float b) { const f2_t v = {a, b}; return __builtin_bit_cast(unsigned, __builtin_convertvector(v, bf2_t)); }
; DI void phase8(const Params& P, char* smem) {
;     ...
;     gemm_tile256(h1b + (long)brow * 1024, 1024, WqT + (long)bcol * 1024, 1024, 32, smem, [&](int row, int col0, f32x4 v) {
;       *reinterpret_cast<uint2*>(Qp + (long)(brow + row) * 2048 + bcol + col0) = make_uint2(pack2bf(v[0], v[1]), pack2bf(v[2], v[3]));
;     });
	ds_read_b128 v[194:197], v236 offset:0
	ds_read_b128 v[198:201], v236 offset:1024
	ds_read_b128 v[202:205], v236 offset:2048
	ds_read_b128 v[212:215], v236 offset:3072
	s_waitcnt lgkmcnt(3)
	global_store_dwordx4 v[238:239], v[194:197], off
	s_nop 0
	v_lshl_add_u64 v[238:239], v[238:239], 0, s[28:29]
	s_waitcnt lgkmcnt(2)
	global_store_dwordx4 v[240:241], v[198:201], off
	s_nop 0
	v_lshl_add_u64 v[240:241], v[240:241], 0, s[28:29]
	s_waitcnt lgkmcnt(1)
	global_store_dwordx4 v[238:239], v[202:205], off
	s_nop 0
	v_lshl_add_u64 v[238:239], v[238:239], 0, s[28:29]
	s_waitcnt lgkmcnt(0)
	global_store_dwordx4 v[240:241], v[212:215], off
	s_nop 0
	v_lshl_add_u64 v[240:241], v[240:241], 0, s[28:29]
	ds_read_b128 v[216:219], v236 offset:4096
	ds_read_b128 v[220:223], v236 offset:5120
	ds_read_b128 v[244:247], v236 offset:6144
	ds_read_b128 v[248:251], v236 offset:7168
	s_waitcnt lgkmcnt(3)
	global_store_dwordx4 v[238:239], v[216:219], off
	s_nop 0
	v_lshl_add_u64 v[238:239], v[238:239], 0, s[28:29]
	s_waitcnt lgkmcnt(2)
	global_store_dwordx4 v[240:241], v[220:223], off
	s_nop 0
	v_lshl_add_u64 v[240:241], v[240:241], 0, s[28:29]
	s_waitcnt lgkmcnt(1)
	global_store_dwordx4 v[238:239], v[244:247], off
	s_nop 0
	v_lshl_add_u64 v[238:239], v[238:239], 0, s[28:29]
	s_waitcnt lgkmcnt(0)
	global_store_dwordx4 v[240:241], v[248:251], off
	s_nop 0
	v_lshl_add_u64 v[240:241], v[240:241], 0, s[28:29]
	ds_read_b128 v[194:197], v236 offset:8192
	ds_read_b128 v[198:201], v236 offset:9216
	ds_read_b128 v[202:205], v236 offset:10240
	ds_read_b128 v[212:215], v236 offset:11264
	s_waitcnt lgkmcnt(3)
	global_store_dwordx4 v[238:239], v[194:197], off
	s_nop 0
	v_lshl_add_u64 v[238:239], v[238:239], 0, s[28:29]
	s_waitcnt lgkmcnt(2)
	global_store_dwordx4 v[240:241], v[198:201], off
	s_nop 0
	v_lshl_add_u64 v[240:241], v[240:241], 0, s[28:29]
	s_waitcnt lgkmcnt(1)
	global_store_dwordx4 v[238:239], v[202:205], off
	s_nop 0
	v_lshl_add_u64 v[238:239], v[238:239], 0, s[28:29]
	s_waitcnt lgkmcnt(0)
	global_store_dwordx4 v[240:241], v[212:215], off
	s_nop 0
	v_lshl_add_u64 v[240:241], v[240:241], 0, s[28:29]
	ds_read_b128 v[216:219], v236 offset:12288
	ds_read_b128 v[220:223], v236 offset:13312
	ds_read_b128 v[244:247], v236 offset:14336
	ds_read_b128 v[248:251], v236 offset:15360
	s_waitcnt lgkmcnt(3)
	global_store_dwordx4 v[238:239], v[216:219], off
	s_nop 0
	v_lshl_add_u64 v[238:239], v[238:239], 0, s[28:29]
	s_waitcnt lgkmcnt(2)
	global_store_dwordx4 v[240:241], v[220:223], off
	s_nop 0
	v_lshl_add_u64 v[240:241], v[240:241], 0, s[28:29]
	s_waitcnt lgkmcnt(1)
	global_store_dwordx4 v[238:239], v[244:247], off
	s_nop 0
	v_lshl_add_u64 v[238:239], v[238:239], 0, s[28:29]
	s_waitcnt lgkmcnt(0)
	global_store_dwordx4 v[240:241], v[248:251], off
	s_nop 0
	v_lshl_add_u64 v[240:241], v[240:241], 0, s[28:29]
	s_add_i32 s75, s75, s5
	s_add_i32 s6, s6, s8
	s_cmpk_lt_i32 s75, 0x80
	s_cbranch_scc1 .LBB0_1068
